# inverse flips: s_setprio 1 during the K-loop load segments (ds_read + LDS-DMA issue), 0 during the MFMA segments, in all four GEMM loops
# baseline (speedup 1.0000x reference)
; #define PG8_STAGE(bufoff, gbase, voff) do { _Pragma("unroll") for (int _i = 0; _i < 2; ++_i) \
;         __builtin_amdgcn_global_load_lds((const unsigned*)((const char*)(gbase) + (voff)[_i]), (PG8_LAS unsigned*)(lds + (bufoff) + ldsw + _i * 8192), 16, 0, 0); } while (0)
; #define PG8_LDA(dst, b, h) do { _Pragma("unroll") for (int m = 0; m < 4; ++m) _Pragma("unroll") for (int k = 0; k < 2; ++k) dst[m][k] = *(const PG8_LAS bf16x8*)(lds + PG8_SA(b, h) + aoff + m * 2048 + k * 1024); } while (0)
; #define PG8_LDB(dst, b, h) do { _Pragma("unroll") for (int n = 0; n < 2; ++n) _Pragma("unroll") for (int k = 0; k < 2; ++k) dst[n][k] = *(const PG8_LAS bf16x8*)(lds + PG8_SB(b, h) + boff + n * 2048 + k * 1024); } while (0)
; #define PG8_MMA(ai, bj, At, Bt) do { __builtin_amdgcn_s_setprio(1); _Pragma("unroll") for (int m = 0; m < 4; ++m) _Pragma("unroll") for (int n = 0; n < 2; ++n) _Pragma("unroll") for (int k = 0; k < 2; ++k) \
;         acc[ai][bj][m][n] = __builtin_amdgcn_mfma_f32_16x16x32_bf16(Bt[n][k], At[m][k], acc[ai][bj][m][n], 0, 0, 0); __builtin_amdgcn_s_setprio(0); } while (0)
; #define PG8_WAIT_V(n) asm volatile("s_waitcnt vmcnt(" #n ")" ::: "memory")
; #define PG8_WAIT_L(n) asm volatile("s_waitcnt lgkmcnt(" #n ")" ::: "memory")
; template <class Epi, class Sched, bool ALIGN_EPI = false, bool SP2 = false>
; __device__ __forceinline__ void gemm_phase(PG8_LAS unsigned char* lds, const Gemm g, const Sched& S, const Epi& E) {
;     ...
;             const bool last = (t == nt - 2);
;             const char* a1 = cA + (size_t)(t + 1) * kstep;
;             const char* a2 = last ? nA : cA + (size_t)(t + 2) * kstep; const char* b2 = last ? nB : cB + (size_t)(t + 2) * kstep;
;             const char* a3 = a2 + kstep; const char* b3 = b2 + kstep;
;             if (last && has_next) S.a_ready(nxt);
;             if constexpr (SP2) {
;             PG8_LDB(B0, 0, 0); PG8_LDB(B1, 0, 1); PG8_SCHED; PG8_LDA(At, 0, 0); PG8_STAGE(PG8_SA(1, 1), a1 + hstep, voffA);
;             PG8_WAIT_V(8); PG8_WAIT_L(0); PG8_BAR; PG8_MMA(0, 0, At, B0); PG8_MMA(0, 1, At, B1); PG8_BAR; PG8_SCHED;
;             PG8_LDA(At, 0, 1); PG8_STAGE(PG8_SB(0, 0), b2, voffB); PG8_STAGE(PG8_SB(0, 1), b2 + hstep, voffB); PG8_STAGE(PG8_SA(0, 0), a2, voffA);
;             PG8_WAIT_V(8); PG8_WAIT_L(0); PG8_BAR; PG8_MMA(1, 0, At, B0); PG8_MMA(1, 1, At, B1); PG8_BAR; PG8_SCHED;
.LBB0_68:
	ds_read_b128 v[128:131], v203
	ds_read_b128 v[132:135], v203 offset:1024
	ds_read_b128 v[136:139], v203 offset:2048
	ds_read_b128 v[140:143], v203 offset:3072
	ds_read_b128 v[144:147], v204
	ds_read_b128 v[148:151], v204 offset:1024
	ds_read_b128 v[180:183], v204 offset:2048
	ds_read_b128 v[184:187], v204 offset:3072
	s_add_u32 s30, s82, 0xfff80080
	s_addc_u32 s31, s83, -1
	s_cmp_eq_u32 s29, 28
	s_cselect_b32 s87, s1, s31
	s_cselect_b32 s86, s75, s30
	s_cselect_b32 s85, s73, vcc_hi
	s_cselect_b32 s84, s81, vcc_lo
	s_add_i32 m0, s94, 0xc000
	ds_read_b128 v[206:209], v205
	ds_read_b128 v[210:213], v205 offset:1024
	ds_read_b128 v[214:217], v205 offset:2048
	ds_read_b128 v[218:221], v205 offset:3072
	ds_read_b128 v[222:225], v205 offset:4096
	ds_read_b128 v[226:229], v205 offset:5120
	ds_read_b128 v[230:233], v205 offset:6144
	ds_read_b128 v[234:237], v205 offset:7168
	global_load_lds_dwordx4 v170, s[82:83]
	s_add_i32 m0, s94, 0xe000
	s_nop 0
	global_load_lds_dwordx4 v172, s[82:83]
	s_waitcnt vmcnt(8)
	s_waitcnt lgkmcnt(0)
	s_setprio 0
	s_barrier
	s_waitcnt lgkmcnt(0)
	v_mfma_f32_16x16x32_bf16 v[124:127], v[128:131], v[206:209], v[124:127]
	v_mfma_f32_16x16x32_bf16 v[120:123], v[136:139], v[206:209], v[120:123]
	v_mfma_f32_16x16x32_bf16 v[116:119], v[128:131], v[214:217], v[116:119]
	v_mfma_f32_16x16x32_bf16 v[112:115], v[136:139], v[214:217], v[112:115]
	v_mfma_f32_16x16x32_bf16 v[108:111], v[128:131], v[222:225], v[108:111]
	v_mfma_f32_16x16x32_bf16 v[104:107], v[136:139], v[222:225], v[104:107]
	v_mfma_f32_16x16x32_bf16 v[100:103], v[128:131], v[230:233], v[100:103]
	v_mfma_f32_16x16x32_bf16 v[96:99], v[136:139], v[230:233], v[96:99]
	v_mfma_f32_16x16x32_bf16 v[124:127], v[132:135], v[210:213], v[124:127]
	v_mfma_f32_16x16x32_bf16 v[120:123], v[140:143], v[210:213], v[120:123]
	v_mfma_f32_16x16x32_bf16 v[116:119], v[132:135], v[218:221], v[116:119]
	v_mfma_f32_16x16x32_bf16 v[112:115], v[140:143], v[218:221], v[112:115]
	v_mfma_f32_16x16x32_bf16 v[108:111], v[132:135], v[226:229], v[108:111]
	v_mfma_f32_16x16x32_bf16 v[104:107], v[140:143], v[226:229], v[104:107]
	v_mfma_f32_16x16x32_bf16 v[100:103], v[132:135], v[234:237], v[100:103]
	v_mfma_f32_16x16x32_bf16 v[96:99], v[140:143], v[234:237], v[96:99]
	v_mfma_f32_16x16x32_bf16 v[68:71], v[144:147], v[206:209], v[68:71]
	v_mfma_f32_16x16x32_bf16 v[64:67], v[180:183], v[206:209], v[64:67]
	v_mfma_f32_16x16x32_bf16 v[52:55], v[144:147], v[214:217], v[52:55]
	v_mfma_f32_16x16x32_bf16 v[48:51], v[180:183], v[214:217], v[48:51]
	v_mfma_f32_16x16x32_bf16 v[44:47], v[144:147], v[222:225], v[44:47]
	v_mfma_f32_16x16x32_bf16 v[40:43], v[180:183], v[222:225], v[40:43]
	v_mfma_f32_16x16x32_bf16 v[36:39], v[144:147], v[230:233], v[36:39]
	v_mfma_f32_16x16x32_bf16 v[32:35], v[180:183], v[230:233], v[32:35]
	v_mfma_f32_16x16x32_bf16 v[68:71], v[148:151], v[210:213], v[68:71]
	v_mfma_f32_16x16x32_bf16 v[64:67], v[184:187], v[210:213], v[64:67]
	v_mfma_f32_16x16x32_bf16 v[52:55], v[148:151], v[218:221], v[52:55]
	v_mfma_f32_16x16x32_bf16 v[48:51], v[184:187], v[218:221], v[48:51]
	v_mfma_f32_16x16x32_bf16 v[44:47], v[148:151], v[226:229], v[44:47]
	v_mfma_f32_16x16x32_bf16 v[40:43], v[184:187], v[226:229], v[40:43]
	v_mfma_f32_16x16x32_bf16 v[36:39], v[148:151], v[234:237], v[36:39]
	v_mfma_f32_16x16x32_bf16 v[32:35], v[184:187], v[234:237], v[32:35]
	s_barrier
	s_setprio 1
	s_add_i32 s30, s47, s92
	s_mov_b32 m0, s30
	ds_read_b128 v[206:209], v205 offset:16384
	ds_read_b128 v[210:213], v205 offset:17408
	ds_read_b128 v[214:217], v205 offset:18432
	ds_read_b128 v[218:221], v205 offset:19456
	ds_read_b128 v[222:225], v205 offset:20480
	ds_read_b128 v[226:229], v205 offset:21504
	ds_read_b128 v[230:233], v205 offset:22528
	ds_read_b128 v[234:237], v205 offset:23552
	global_load_lds_dwordx4 v158, s[84:85]
	s_add_i32 m0, s30, 0x2000
	s_add_u32 s30, s84, 0x80000
	s_addc_u32 s31, s85, 0
	s_add_i32 s89, s33, s92
	global_load_lds_dwordx4 v154, s[84:85]
	s_mov_b32 m0, s89
	s_nop 0
	global_load_lds_dwordx4 v158, s[30:31]
	s_add_i32 m0, s89, 0x2000
	s_nop 0
	global_load_lds_dwordx4 v154, s[30:31]
	s_mov_b32 m0, s94
	s_nop 0
	global_load_lds_dwordx4 v160, s[86:87]
	s_mov_b32 m0, s95
	s_nop 0
	global_load_lds_dwordx4 v156, s[86:87]
	s_waitcnt vmcnt(8)
	s_waitcnt lgkmcnt(0)
	s_setprio 0
	s_barrier
	s_waitcnt lgkmcnt(0)
	v_mfma_f32_16x16x32_bf16 v[92:95], v[128:131], v[206:209], v[92:95]
	v_mfma_f32_16x16x32_bf16 v[88:91], v[136:139], v[206:209], v[88:91]
	v_mfma_f32_16x16x32_bf16 v[84:87], v[128:131], v[214:217], v[84:87]
	v_mfma_f32_16x16x32_bf16 v[80:83], v[136:139], v[214:217], v[80:83]
	v_mfma_f32_16x16x32_bf16 v[76:79], v[128:131], v[222:225], v[76:79]
	v_mfma_f32_16x16x32_bf16 v[72:75], v[136:139], v[222:225], v[72:75]
	v_mfma_f32_16x16x32_bf16 v[60:63], v[128:131], v[230:233], v[60:63]
	v_mfma_f32_16x16x32_bf16 v[56:59], v[136:139], v[230:233], v[56:59]
	v_mfma_f32_16x16x32_bf16 v[92:95], v[132:135], v[210:213], v[92:95]
	v_mfma_f32_16x16x32_bf16 v[88:91], v[140:143], v[210:213], v[88:91]
	v_mfma_f32_16x16x32_bf16 v[84:87], v[132:135], v[218:221], v[84:87]
	v_mfma_f32_16x16x32_bf16 v[80:83], v[140:143], v[218:221], v[80:83]
	v_mfma_f32_16x16x32_bf16 v[76:79], v[132:135], v[226:229], v[76:79]
	v_mfma_f32_16x16x32_bf16 v[72:75], v[140:143], v[226:229], v[72:75]
	v_mfma_f32_16x16x32_bf16 v[60:63], v[132:135], v[234:237], v[60:63]
	v_mfma_f32_16x16x32_bf16 v[56:59], v[140:143], v[234:237], v[56:59]
	v_mfma_f32_16x16x32_bf16 v[28:31], v[144:147], v[206:209], v[28:31]
	v_mfma_f32_16x16x32_bf16 v[24:27], v[180:183], v[206:209], v[24:27]
	v_mfma_f32_16x16x32_bf16 v[20:23], v[144:147], v[214:217], v[20:23]
	v_mfma_f32_16x16x32_bf16 v[16:19], v[180:183], v[214:217], v[16:19]
	v_mfma_f32_16x16x32_bf16 v[12:15], v[144:147], v[222:225], v[12:15]
	v_mfma_f32_16x16x32_bf16 v[8:11], v[180:183], v[222:225], v[8:11]
	v_mfma_f32_16x16x32_bf16 v[4:7], v[144:147], v[230:233], v[4:7]
	v_mfma_f32_16x16x32_bf16 v[0:3], v[180:183], v[230:233], v[0:3]
	v_mfma_f32_16x16x32_bf16 v[28:31], v[148:151], v[210:213], v[28:31]
	v_mfma_f32_16x16x32_bf16 v[24:27], v[184:187], v[210:213], v[24:27]
	v_mfma_f32_16x16x32_bf16 v[20:23], v[148:151], v[218:221], v[20:23]
	v_mfma_f32_16x16x32_bf16 v[16:19], v[184:187], v[218:221], v[16:19]
	v_mfma_f32_16x16x32_bf16 v[12:15], v[148:151], v[226:229], v[12:15]
	v_mfma_f32_16x16x32_bf16 v[8:11], v[184:187], v[226:229], v[8:11]
	v_mfma_f32_16x16x32_bf16 v[4:7], v[148:151], v[234:237], v[4:7]
	v_mfma_f32_16x16x32_bf16 v[0:3], v[184:187], v[234:237], v[0:3]
	s_barrier
; #define PG8_STAGE(bufoff, gbase, voff) do { _Pragma("unroll") for (int _i = 0; _i < 2; ++_i) \
;         __builtin_amdgcn_global_load_lds((const unsigned*)((const char*)(gbase) + (voff)[_i]), (PG8_LAS unsigned*)(lds + (bufoff) + ldsw + _i * 8192), 16, 0, 0); } while (0)
; #define PG8_LDA(dst, b, h) do { _Pragma("unroll") for (int m = 0; m < 4; ++m) _Pragma("unroll") for (int k = 0; k < 2; ++k) dst[m][k] = *(const PG8_LAS bf16x8*)(lds + PG8_SA(b, h) + aoff + m * 2048 + k * 1024); } while (0)
; #define PG8_LDB(dst, b, h) do { _Pragma("unroll") for (int n = 0; n < 2; ++n) _Pragma("unroll") for (int k = 0; k < 2; ++k) dst[n][k] = *(const PG8_LAS bf16x8*)(lds + PG8_SB(b, h) + boff + n * 2048 + k * 1024); } while (0)
; #define PG8_MMA(ai, bj, At, Bt) do { __builtin_amdgcn_s_setprio(1); _Pragma("unroll") for (int m = 0; m < 4; ++m) _Pragma("unroll") for (int n = 0; n < 2; ++n) _Pragma("unroll") for (int k = 0; k < 2; ++k) \
;         acc[ai][bj][m][n] = __builtin_amdgcn_mfma_f32_16x16x32_bf16(Bt[n][k], At[m][k], acc[ai][bj][m][n], 0, 0, 0); __builtin_amdgcn_s_setprio(0); } while (0)
; #define PG8_WAIT_V(n) asm volatile("s_waitcnt vmcnt(" #n ")" ::: "memory")
; #define PG8_WAIT_L(n) asm volatile("s_waitcnt lgkmcnt(" #n ")" ::: "memory")
; #define PG8_BAR __builtin_amdgcn_s_barrier()
; #define PG8_SCHED __builtin_amdgcn_sched_barrier(0)
; template <class Epi, class Sched, bool ALIGN_EPI = false, bool SP2 = false>
; __device__ __forceinline__ void gemm_phase(PG8_LAS unsigned char* lds, const Gemm g, const Sched& S, const Epi& E) {
;     ...
;         for (int t = 0; t < nt; t += 2) {
;             const bool last = (t == nt - 2);
;             const char* a1 = cA + (size_t)(t + 1) * kstep;
;             const char* a2 = last ? nA : cA + (size_t)(t + 2) * kstep; const char* b2 = last ? nB : cB + (size_t)(t + 2) * kstep;
;     ...
;             PG8_LDB(B0, 1, 0); PG8_LDB(B1, 1, 1); PG8_SCHED; PG8_LDA(At, 1, 0); PG8_STAGE(PG8_SA(0, 1), a2 + hstep, voffA);
;             PG8_WAIT_V(8); PG8_WAIT_L(0); PG8_BAR; PG8_MMA(0, 0, At, B0); PG8_MMA(0, 1, At, B1); PG8_BAR; PG8_SCHED;
;             PG8_LDA(At, 1, 1); PG8_STAGE(PG8_SB(1, 0), b3, voffB); PG8_STAGE(PG8_SB(1, 1), b3 + hstep, voffB); PG8_STAGE(PG8_SA(1, 0), a3, voffA);
;             PG8_WAIT_V(8); PG8_WAIT_L(0); PG8_BAR; PG8_MMA(1, 0, At, B0); PG8_MMA(1, 1, At, B1); PG8_BAR; PG8_SCHED;
	s_setprio 1
	s_add_i32 s89, 0, 0x18000
	s_add_i32 s54, 0, 0x1c000
	v_add_u32_e32 v140, s89, v190
	v_add_u32_e32 v162, s54, v190
	ds_read_b128 v[128:131], v140
	ds_read_b128 v[132:135], v140 offset:1024
	ds_read_b128 v[136:139], v140 offset:2048
	ds_read_b128 v[140:143], v140 offset:3072
	ds_read_b128 v[144:147], v162
	ds_read_b128 v[148:151], v162 offset:1024
	ds_read_b128 v[180:183], v162 offset:2048
	ds_read_b128 v[184:187], v162 offset:3072
	s_add_u32 s30, s86, 0x80000
	s_addc_u32 s31, s87, 0
	s_mov_b32 m0, s96
	ds_read_b128 v[206:209], v205 offset:32768
	ds_read_b128 v[210:213], v205 offset:33792
	ds_read_b128 v[214:217], v205 offset:34816
	ds_read_b128 v[218:221], v205 offset:35840
	ds_read_b128 v[222:225], v205 offset:36864
	ds_read_b128 v[226:229], v205 offset:37888
	ds_read_b128 v[230:233], v205 offset:38912
	ds_read_b128 v[234:237], v205 offset:39936
	global_load_lds_dwordx4 v160, s[30:31]
	s_mov_b32 m0, s97
	s_nop 0
	global_load_lds_dwordx4 v156, s[30:31]
	s_waitcnt vmcnt(8)
	s_waitcnt lgkmcnt(0)
	s_setprio 0
	s_barrier
	s_waitcnt lgkmcnt(0)
	v_mfma_f32_16x16x32_bf16 v[124:127], v[128:131], v[206:209], v[124:127]
	v_mfma_f32_16x16x32_bf16 v[120:123], v[136:139], v[206:209], v[120:123]
	v_mfma_f32_16x16x32_bf16 v[116:119], v[128:131], v[214:217], v[116:119]
	v_mfma_f32_16x16x32_bf16 v[112:115], v[136:139], v[214:217], v[112:115]
	v_mfma_f32_16x16x32_bf16 v[108:111], v[128:131], v[222:225], v[108:111]
	v_mfma_f32_16x16x32_bf16 v[104:107], v[136:139], v[222:225], v[104:107]
	v_mfma_f32_16x16x32_bf16 v[100:103], v[128:131], v[230:233], v[100:103]
	v_mfma_f32_16x16x32_bf16 v[96:99], v[136:139], v[230:233], v[96:99]
	v_mfma_f32_16x16x32_bf16 v[124:127], v[132:135], v[210:213], v[124:127]
	v_mfma_f32_16x16x32_bf16 v[120:123], v[140:143], v[210:213], v[120:123]
	v_mfma_f32_16x16x32_bf16 v[116:119], v[132:135], v[218:221], v[116:119]
	v_mfma_f32_16x16x32_bf16 v[112:115], v[140:143], v[218:221], v[112:115]
	v_mfma_f32_16x16x32_bf16 v[108:111], v[132:135], v[226:229], v[108:111]
	v_mfma_f32_16x16x32_bf16 v[104:107], v[140:143], v[226:229], v[104:107]
	v_mfma_f32_16x16x32_bf16 v[100:103], v[132:135], v[234:237], v[100:103]
	v_mfma_f32_16x16x32_bf16 v[96:99], v[140:143], v[234:237], v[96:99]
	v_mfma_f32_16x16x32_bf16 v[68:71], v[144:147], v[206:209], v[68:71]
	v_mfma_f32_16x16x32_bf16 v[64:67], v[180:183], v[206:209], v[64:67]
	v_mfma_f32_16x16x32_bf16 v[52:55], v[144:147], v[214:217], v[52:55]
	v_mfma_f32_16x16x32_bf16 v[48:51], v[180:183], v[214:217], v[48:51]
	v_mfma_f32_16x16x32_bf16 v[44:47], v[144:147], v[222:225], v[44:47]
	v_mfma_f32_16x16x32_bf16 v[40:43], v[180:183], v[222:225], v[40:43]
	v_mfma_f32_16x16x32_bf16 v[36:39], v[144:147], v[230:233], v[36:39]
	v_mfma_f32_16x16x32_bf16 v[32:35], v[180:183], v[230:233], v[32:35]
	v_mfma_f32_16x16x32_bf16 v[68:71], v[148:151], v[210:213], v[68:71]
	v_mfma_f32_16x16x32_bf16 v[64:67], v[184:187], v[210:213], v[64:67]
	v_mfma_f32_16x16x32_bf16 v[52:55], v[148:151], v[218:221], v[52:55]
	v_mfma_f32_16x16x32_bf16 v[48:51], v[184:187], v[218:221], v[48:51]
	v_mfma_f32_16x16x32_bf16 v[44:47], v[148:151], v[226:229], v[44:47]
	v_mfma_f32_16x16x32_bf16 v[40:43], v[184:187], v[226:229], v[40:43]
	v_mfma_f32_16x16x32_bf16 v[36:39], v[148:151], v[234:237], v[36:39]
	v_mfma_f32_16x16x32_bf16 v[32:35], v[184:187], v[234:237], v[32:35]
	s_barrier
	s_setprio 1
	s_add_i32 s30, s89, s92
	s_mov_b32 m0, s30
	ds_read_b128 v[206:209], v205 offset:49152
	ds_read_b128 v[210:213], v205 offset:50176
	ds_read_b128 v[214:217], v205 offset:51200
	ds_read_b128 v[218:221], v205 offset:52224
	ds_read_b128 v[222:225], v205 offset:53248
	ds_read_b128 v[226:229], v205 offset:54272
	ds_read_b128 v[230:233], v205 offset:55296
	ds_read_b128 v[234:237], v205 offset:56320
	s_add_u32 s62, s84, 0x80
	s_addc_u32 s63, s85, 0
	global_load_lds_dwordx4 v158, s[62:63]
	s_add_i32 m0, s30, 0x2000
	s_add_u32 s30, s84, 0x80080
	s_addc_u32 s31, s85, 0
	s_add_i32 s54, s54, s92
	global_load_lds_dwordx4 v154, s[62:63]
	s_mov_b32 m0, s54
	s_nop 0
	global_load_lds_dwordx4 v158, s[30:31]
	s_add_i32 m0, s54, 0x2000
	s_nop 0
	global_load_lds_dwordx4 v154, s[30:31]
	s_mov_b32 m0, s88
	s_nop 0
	s_add_u32 s62, s86, 0x80
	s_addc_u32 s63, s87, 0
	global_load_lds_dwordx4 v160, s[62:63]
	s_mov_b32 m0, s46
	s_nop 0
	global_load_lds_dwordx4 v156, s[62:63]
	s_waitcnt vmcnt(8)
	s_waitcnt lgkmcnt(0)
	s_setprio 0
	s_barrier
	s_waitcnt lgkmcnt(0)
	v_mfma_f32_16x16x32_bf16 v[92:95], v[128:131], v[206:209], v[92:95]
	v_mfma_f32_16x16x32_bf16 v[88:91], v[136:139], v[206:209], v[88:91]
	v_mfma_f32_16x16x32_bf16 v[84:87], v[128:131], v[214:217], v[84:87]
	v_mfma_f32_16x16x32_bf16 v[80:83], v[136:139], v[214:217], v[80:83]
	v_mfma_f32_16x16x32_bf16 v[76:79], v[128:131], v[222:225], v[76:79]
	v_mfma_f32_16x16x32_bf16 v[72:75], v[136:139], v[222:225], v[72:75]
	v_mfma_f32_16x16x32_bf16 v[60:63], v[128:131], v[230:233], v[60:63]
	v_mfma_f32_16x16x32_bf16 v[56:59], v[136:139], v[230:233], v[56:59]
	v_mfma_f32_16x16x32_bf16 v[92:95], v[132:135], v[210:213], v[92:95]
	v_mfma_f32_16x16x32_bf16 v[88:91], v[140:143], v[210:213], v[88:91]
	v_mfma_f32_16x16x32_bf16 v[84:87], v[132:135], v[218:221], v[84:87]
	v_mfma_f32_16x16x32_bf16 v[80:83], v[140:143], v[218:221], v[80:83]
	v_mfma_f32_16x16x32_bf16 v[76:79], v[132:135], v[226:229], v[76:79]
	v_mfma_f32_16x16x32_bf16 v[72:75], v[140:143], v[226:229], v[72:75]
	v_mfma_f32_16x16x32_bf16 v[60:63], v[132:135], v[234:237], v[60:63]
	v_mfma_f32_16x16x32_bf16 v[56:59], v[140:143], v[234:237], v[56:59]
	v_mfma_f32_16x16x32_bf16 v[28:31], v[144:147], v[206:209], v[28:31]
	v_mfma_f32_16x16x32_bf16 v[24:27], v[180:183], v[206:209], v[24:27]
	v_mfma_f32_16x16x32_bf16 v[20:23], v[144:147], v[214:217], v[20:23]
	v_mfma_f32_16x16x32_bf16 v[16:19], v[180:183], v[214:217], v[16:19]
	v_mfma_f32_16x16x32_bf16 v[12:15], v[144:147], v[222:225], v[12:15]
	v_mfma_f32_16x16x32_bf16 v[8:11], v[180:183], v[222:225], v[8:11]
	v_mfma_f32_16x16x32_bf16 v[4:7], v[144:147], v[230:233], v[4:7]
	v_mfma_f32_16x16x32_bf16 v[0:3], v[180:183], v[230:233], v[0:3]
	v_mfma_f32_16x16x32_bf16 v[28:31], v[148:151], v[210:213], v[28:31]
	v_mfma_f32_16x16x32_bf16 v[24:27], v[184:187], v[210:213], v[24:27]
	v_mfma_f32_16x16x32_bf16 v[20:23], v[148:151], v[218:221], v[20:23]
	v_mfma_f32_16x16x32_bf16 v[16:19], v[184:187], v[218:221], v[16:19]
	v_mfma_f32_16x16x32_bf16 v[12:15], v[148:151], v[226:229], v[12:15]
	v_mfma_f32_16x16x32_bf16 v[8:11], v[184:187], v[226:229], v[8:11]
	v_mfma_f32_16x16x32_bf16 v[4:7], v[148:151], v[234:237], v[4:7]
	v_mfma_f32_16x16x32_bf16 v[0:3], v[184:187], v[234:237], v[0:3]
	s_barrier
	s_setprio 1
	s_add_i32 s29, s29, 2
	s_add_u32 s82, s82, 0x100
	s_addc_u32 s83, s83, 0
	s_add_u32 vcc_lo, vcc_lo, 0x100
	s_addc_u32 vcc_hi, vcc_hi, 0
	s_cmp_gt_u32 s29, 29
	s_cbranch_scc0 .LBB0_68
	s_and_b64 vcc, exec, s[64:65]
	s_cbranch_vccz .LBB0_71
	s_barrier

; #define PG8_STAGE(bufoff, gbase, voff) do { _Pragma("unroll") for (int _i = 0; _i < 2; ++_i) \
;         __builtin_amdgcn_global_load_lds((const unsigned*)((const char*)(gbase) + (voff)[_i]), (PG8_LAS unsigned*)(lds + (bufoff) + ldsw + _i * 8192), 16, 0, 0); } while (0)
; #define PG8_LDA(dst, b, h) do { _Pragma("unroll") for (int m = 0; m < 4; ++m) _Pragma("unroll") for (int k = 0; k < 2; ++k) dst[m][k] = *(const PG8_LAS bf16x8*)(lds + PG8_SA(b, h) + aoff + m * 2048 + k * 1024); } while (0)
; #define PG8_LDB(dst, b, h) do { _Pragma("unroll") for (int n = 0; n < 2; ++n) _Pragma("unroll") for (int k = 0; k < 2; ++k) dst[n][k] = *(const PG8_LAS bf16x8*)(lds + PG8_SB(b, h) + boff + n * 2048 + k * 1024); } while (0)
; #define PG8_MMA(ai, bj, At, Bt) do { __builtin_amdgcn_s_setprio(1); _Pragma("unroll") for (int m = 0; m < 4; ++m) _Pragma("unroll") for (int n = 0; n < 2; ++n) _Pragma("unroll") for (int k = 0; k < 2; ++k) \
;         acc[ai][bj][m][n] = __builtin_amdgcn_mfma_f32_16x16x32_bf16(Bt[n][k], At[m][k], acc[ai][bj][m][n], 0, 0, 0); __builtin_amdgcn_s_setprio(0); } while (0)
; #define PG8_WAIT_V(n) asm volatile("s_waitcnt vmcnt(" #n ")" ::: "memory")
; #define PG8_WAIT_L(n) asm volatile("s_waitcnt lgkmcnt(" #n ")" ::: "memory")
; template <class Epi, class Sched, bool ALIGN_EPI = false, bool SP2 = false>
; __device__ __forceinline__ void gemm_phase(PG8_LAS unsigned char* lds, const Gemm g, const Sched& S, const Epi& E) {
;     ...
;             const bool last = (t == nt - 2);
;             const char* a1 = cA + (size_t)(t + 1) * kstep;
;             const char* a2 = last ? nA : cA + (size_t)(t + 2) * kstep; const char* b2 = last ? nB : cB + (size_t)(t + 2) * kstep;
;             const char* a3 = a2 + kstep; const char* b3 = b2 + kstep;
;             if (last && has_next) S.a_ready(nxt);
;             if constexpr (SP2) {
;             PG8_LDB(B0, 0, 0); PG8_LDB(B1, 0, 1); PG8_SCHED; PG8_LDA(At, 0, 0); PG8_STAGE(PG8_SA(1, 1), a1 + hstep, voffA);
;             PG8_WAIT_V(8); PG8_WAIT_L(0); PG8_BAR; PG8_MMA(0, 0, At, B0); PG8_MMA(0, 1, At, B1); PG8_BAR; PG8_SCHED;
;             PG8_LDA(At, 0, 1); PG8_STAGE(PG8_SB(0, 0), b2, voffB); PG8_STAGE(PG8_SB(0, 1), b2 + hstep, voffB); PG8_STAGE(PG8_SA(0, 0), a2, voffA);
;             PG8_WAIT_V(8); PG8_WAIT_L(0); PG8_BAR; PG8_MMA(1, 0, At, B0); PG8_MMA(1, 1, At, B1); PG8_BAR; PG8_SCHED;
.LBB0_283:
	ds_read_b128 v[152:155], v149
	ds_read_b128 v[156:159], v149 offset:1024
	ds_read_b128 v[160:163], v149 offset:2048
	ds_read_b128 v[164:167], v149 offset:3072
	ds_read_b128 v[168:171], v150
	ds_read_b128 v[172:175], v150 offset:1024
	ds_read_b128 v[180:183], v150 offset:2048
	ds_read_b128 v[184:187], v150 offset:3072
	s_add_u32 s30, s66, 0xfff80080
	s_addc_u32 s31, s67, -1
	s_cmp_eq_u32 s85, 28
	s_cselect_b32 s71, s59, s31
	s_cselect_b32 s70, s81, s30
	s_cselect_b32 s69, s57, s84
	s_cselect_b32 s68, s82, s83
	s_add_i32 m0, s29, 0xc000
	ds_read_b128 v[188:191], v151
	ds_read_b128 v[192:195], v151 offset:1024
	ds_read_b128 v[196:199], v151 offset:2048
	ds_read_b128 v[200:203], v151 offset:3072
	ds_read_b128 v[204:207], v151 offset:4096
	ds_read_b128 v[208:211], v151 offset:5120
	ds_read_b128 v[212:215], v151 offset:6144
	ds_read_b128 v[216:219], v151 offset:7168
	global_load_lds_dwordx4 v136, s[66:67]
	s_add_i32 m0, s29, 0xe000
	s_nop 0
	global_load_lds_dwordx4 v138, s[66:67]
	s_waitcnt vmcnt(8)
	s_waitcnt lgkmcnt(0)
	s_setprio 0
	s_barrier
	s_waitcnt lgkmcnt(0)
	v_mfma_f32_16x16x32_bf16 v[124:127], v[152:155], v[188:191], v[124:127]
	v_mfma_f32_16x16x32_bf16 v[120:123], v[160:163], v[188:191], v[120:123]
	v_mfma_f32_16x16x32_bf16 v[116:119], v[152:155], v[196:199], v[116:119]
	v_mfma_f32_16x16x32_bf16 v[108:111], v[160:163], v[196:199], v[108:111]
	v_mfma_f32_16x16x32_bf16 v[100:103], v[152:155], v[204:207], v[100:103]
	v_mfma_f32_16x16x32_bf16 v[92:95], v[160:163], v[204:207], v[92:95]
	v_mfma_f32_16x16x32_bf16 v[84:87], v[152:155], v[212:215], v[84:87]
	v_mfma_f32_16x16x32_bf16 v[76:79], v[160:163], v[212:215], v[76:79]
	v_mfma_f32_16x16x32_bf16 v[124:127], v[156:159], v[192:195], v[124:127]
	v_mfma_f32_16x16x32_bf16 v[120:123], v[164:167], v[192:195], v[120:123]
	v_mfma_f32_16x16x32_bf16 v[116:119], v[156:159], v[200:203], v[116:119]
	v_mfma_f32_16x16x32_bf16 v[108:111], v[164:167], v[200:203], v[108:111]
	v_mfma_f32_16x16x32_bf16 v[100:103], v[156:159], v[208:211], v[100:103]
	v_mfma_f32_16x16x32_bf16 v[92:95], v[164:167], v[208:211], v[92:95]
	v_mfma_f32_16x16x32_bf16 v[84:87], v[156:159], v[216:219], v[84:87]
	v_mfma_f32_16x16x32_bf16 v[76:79], v[164:167], v[216:219], v[76:79]
	v_mfma_f32_16x16x32_bf16 v[112:115], v[168:171], v[188:191], v[112:115]
	v_mfma_f32_16x16x32_bf16 v[104:107], v[180:183], v[188:191], v[104:107]
	v_mfma_f32_16x16x32_bf16 v[96:99], v[168:171], v[196:199], v[96:99]
	v_mfma_f32_16x16x32_bf16 v[88:91], v[180:183], v[196:199], v[88:91]
	v_mfma_f32_16x16x32_bf16 v[80:83], v[168:171], v[204:207], v[80:83]
	v_mfma_f32_16x16x32_bf16 v[72:75], v[180:183], v[204:207], v[72:75]
	v_mfma_f32_16x16x32_bf16 v[68:71], v[168:171], v[212:215], v[68:71]
	v_mfma_f32_16x16x32_bf16 v[64:67], v[180:183], v[212:215], v[64:67]
	v_mfma_f32_16x16x32_bf16 v[112:115], v[172:175], v[192:195], v[112:115]
	v_mfma_f32_16x16x32_bf16 v[104:107], v[184:187], v[192:195], v[104:107]
	v_mfma_f32_16x16x32_bf16 v[96:99], v[172:175], v[200:203], v[96:99]
	v_mfma_f32_16x16x32_bf16 v[88:91], v[184:187], v[200:203], v[88:91]
	v_mfma_f32_16x16x32_bf16 v[80:83], v[172:175], v[208:211], v[80:83]
	v_mfma_f32_16x16x32_bf16 v[72:75], v[184:187], v[208:211], v[72:75]
	v_mfma_f32_16x16x32_bf16 v[68:71], v[172:175], v[216:219], v[68:71]
	v_mfma_f32_16x16x32_bf16 v[64:67], v[184:187], v[216:219], v[64:67]
	s_barrier
	s_setprio 1
	s_add_i32 s30, s74, s1
	s_mov_b32 m0, s30
	ds_read_b128 v[188:191], v151 offset:16384
	ds_read_b128 v[192:195], v151 offset:17408
	ds_read_b128 v[196:199], v151 offset:18432
	ds_read_b128 v[200:203], v151 offset:19456
	ds_read_b128 v[204:207], v151 offset:20480
	ds_read_b128 v[208:211], v151 offset:21504
	ds_read_b128 v[212:215], v151 offset:22528
	ds_read_b128 v[216:219], v151 offset:23552
	global_load_lds_dwordx4 v130, s[68:69]
	s_add_i32 m0, s30, 0x2000
	s_add_u32 s30, s68, 0x80000
	s_addc_u32 s31, s69, 0
	s_add_i32 s86, s75, s1
	global_load_lds_dwordx4 v134, s[68:69]
	s_mov_b32 m0, s86
	s_nop 0
	global_load_lds_dwordx4 v130, s[30:31]
	s_add_i32 m0, s86, 0x2000
	s_nop 0
	global_load_lds_dwordx4 v134, s[30:31]
	s_mov_b32 m0, s29
	s_nop 0
	global_load_lds_dwordx4 v128, s[70:71]
	s_mov_b32 m0, s33
	s_nop 0
	global_load_lds_dwordx4 v132, s[70:71]
	s_waitcnt vmcnt(8)
	s_waitcnt lgkmcnt(0)
	s_setprio 0
	s_barrier
	s_waitcnt lgkmcnt(0)
	v_mfma_f32_16x16x32_bf16 v[60:63], v[152:155], v[188:191], v[60:63]
	v_mfma_f32_16x16x32_bf16 v[56:59], v[160:163], v[188:191], v[56:59]
	v_mfma_f32_16x16x32_bf16 v[52:55], v[152:155], v[196:199], v[52:55]
	v_mfma_f32_16x16x32_bf16 v[44:47], v[160:163], v[196:199], v[44:47]
	v_mfma_f32_16x16x32_bf16 v[36:39], v[152:155], v[204:207], v[36:39]
	v_mfma_f32_16x16x32_bf16 v[28:31], v[160:163], v[204:207], v[28:31]
	v_mfma_f32_16x16x32_bf16 v[20:23], v[152:155], v[212:215], v[20:23]
	v_mfma_f32_16x16x32_bf16 v[12:15], v[160:163], v[212:215], v[12:15]
	v_mfma_f32_16x16x32_bf16 v[60:63], v[156:159], v[192:195], v[60:63]
	v_mfma_f32_16x16x32_bf16 v[56:59], v[164:167], v[192:195], v[56:59]
	v_mfma_f32_16x16x32_bf16 v[52:55], v[156:159], v[200:203], v[52:55]
	v_mfma_f32_16x16x32_bf16 v[44:47], v[164:167], v[200:203], v[44:47]
	v_mfma_f32_16x16x32_bf16 v[36:39], v[156:159], v[208:211], v[36:39]
	v_mfma_f32_16x16x32_bf16 v[28:31], v[164:167], v[208:211], v[28:31]
	v_mfma_f32_16x16x32_bf16 v[20:23], v[156:159], v[216:219], v[20:23]
	v_mfma_f32_16x16x32_bf16 v[12:15], v[164:167], v[216:219], v[12:15]
	v_mfma_f32_16x16x32_bf16 v[48:51], v[168:171], v[188:191], v[48:51]
	v_mfma_f32_16x16x32_bf16 v[40:43], v[180:183], v[188:191], v[40:43]
	v_mfma_f32_16x16x32_bf16 v[32:35], v[168:171], v[196:199], v[32:35]
	v_mfma_f32_16x16x32_bf16 v[24:27], v[180:183], v[196:199], v[24:27]
	v_mfma_f32_16x16x32_bf16 v[16:19], v[168:171], v[204:207], v[16:19]
	v_mfma_f32_16x16x32_bf16 v[8:11], v[180:183], v[204:207], v[8:11]
	v_mfma_f32_16x16x32_bf16 v[4:7], v[168:171], v[212:215], v[4:7]
	v_mfma_f32_16x16x32_bf16 v[0:3], v[180:183], v[212:215], v[0:3]
	v_mfma_f32_16x16x32_bf16 v[48:51], v[172:175], v[192:195], v[48:51]
	v_mfma_f32_16x16x32_bf16 v[40:43], v[184:187], v[192:195], v[40:43]
	v_mfma_f32_16x16x32_bf16 v[32:35], v[172:175], v[200:203], v[32:35]
	v_mfma_f32_16x16x32_bf16 v[24:27], v[184:187], v[200:203], v[24:27]
	v_mfma_f32_16x16x32_bf16 v[16:19], v[172:175], v[208:211], v[16:19]
	v_mfma_f32_16x16x32_bf16 v[8:11], v[184:187], v[208:211], v[8:11]
	v_mfma_f32_16x16x32_bf16 v[4:7], v[172:175], v[216:219], v[4:7]
	v_mfma_f32_16x16x32_bf16 v[0:3], v[184:187], v[216:219], v[0:3]
	s_barrier
; #define PG8_STAGE(bufoff, gbase, voff) do { _Pragma("unroll") for (int _i = 0; _i < 2; ++_i) \
;         __builtin_amdgcn_global_load_lds((const unsigned*)((const char*)(gbase) + (voff)[_i]), (PG8_LAS unsigned*)(lds + (bufoff) + ldsw + _i * 8192), 16, 0, 0); } while (0)
; #define PG8_LDA(dst, b, h) do { _Pragma("unroll") for (int m = 0; m < 4; ++m) _Pragma("unroll") for (int k = 0; k < 2; ++k) dst[m][k] = *(const PG8_LAS bf16x8*)(lds + PG8_SA(b, h) + aoff + m * 2048 + k * 1024); } while (0)
; #define PG8_LDB(dst, b, h) do { _Pragma("unroll") for (int n = 0; n < 2; ++n) _Pragma("unroll") for (int k = 0; k < 2; ++k) dst[n][k] = *(const PG8_LAS bf16x8*)(lds + PG8_SB(b, h) + boff + n * 2048 + k * 1024); } while (0)
; #define PG8_MMA(ai, bj, At, Bt) do { __builtin_amdgcn_s_setprio(1); _Pragma("unroll") for (int m = 0; m < 4; ++m) _Pragma("unroll") for (int n = 0; n < 2; ++n) _Pragma("unroll") for (int k = 0; k < 2; ++k) \
;         acc[ai][bj][m][n] = __builtin_amdgcn_mfma_f32_16x16x32_bf16(Bt[n][k], At[m][k], acc[ai][bj][m][n], 0, 0, 0); __builtin_amdgcn_s_setprio(0); } while (0)
; #define PG8_WAIT_V(n) asm volatile("s_waitcnt vmcnt(" #n ")" ::: "memory")
; #define PG8_WAIT_L(n) asm volatile("s_waitcnt lgkmcnt(" #n ")" ::: "memory")
; #define PG8_BAR __builtin_amdgcn_s_barrier()
; #define PG8_SCHED __builtin_amdgcn_sched_barrier(0)
; template <class Epi, class Sched, bool ALIGN_EPI = false, bool SP2 = false>
; __device__ __forceinline__ void gemm_phase(PG8_LAS unsigned char* lds, const Gemm g, const Sched& S, const Epi& E) {
;     ...
;             PG8_LDB(B0, 1, 0); PG8_LDB(B1, 1, 1); PG8_SCHED; PG8_LDA(At, 1, 0); PG8_STAGE(PG8_SA(0, 1), a2 + hstep, voffA);
;             PG8_WAIT_V(8); PG8_WAIT_L(0); PG8_BAR; PG8_MMA(0, 0, At, B0); PG8_MMA(0, 1, At, B1); PG8_BAR; PG8_SCHED;
;             PG8_LDA(At, 1, 1); PG8_STAGE(PG8_SB(1, 0), b3, voffB); PG8_STAGE(PG8_SB(1, 1), b3 + hstep, voffB); PG8_STAGE(PG8_SA(1, 0), a3, voffA);
;             PG8_WAIT_V(8); PG8_WAIT_L(0); PG8_BAR; PG8_MMA(1, 0, At, B0); PG8_MMA(1, 1, At, B1); PG8_BAR; PG8_SCHED;
	s_setprio 1
	s_add_i32 s86, 0, 0x18000
	s_add_i32 s87, 0, 0x1c000
	v_add_u32_e32 v164, s86, v147
	v_add_u32_e32 v179, s87, v147
	ds_read_b128 v[152:155], v164
	ds_read_b128 v[156:159], v164 offset:1024
	ds_read_b128 v[160:163], v164 offset:2048
	ds_read_b128 v[164:167], v164 offset:3072
	ds_read_b128 v[168:171], v179
	ds_read_b128 v[172:175], v179 offset:1024
	ds_read_b128 v[180:183], v179 offset:2048
	ds_read_b128 v[184:187], v179 offset:3072
	s_add_u32 s30, s70, 0x80000
	s_addc_u32 s31, s71, 0
	s_mov_b32 m0, s46
	ds_read_b128 v[188:191], v151 offset:32768
	ds_read_b128 v[192:195], v151 offset:33792
	ds_read_b128 v[196:199], v151 offset:34816
	ds_read_b128 v[200:203], v151 offset:35840
	ds_read_b128 v[204:207], v151 offset:36864
	ds_read_b128 v[208:211], v151 offset:37888
	ds_read_b128 v[212:215], v151 offset:38912
	ds_read_b128 v[216:219], v151 offset:39936
	global_load_lds_dwordx4 v128, s[30:31]
	s_mov_b32 m0, s47
	s_nop 0
	global_load_lds_dwordx4 v132, s[30:31]
	s_waitcnt vmcnt(8)
	s_waitcnt lgkmcnt(0)
	s_setprio 0
	s_barrier
	s_waitcnt lgkmcnt(0)
	v_mfma_f32_16x16x32_bf16 v[124:127], v[152:155], v[188:191], v[124:127]
	v_mfma_f32_16x16x32_bf16 v[120:123], v[160:163], v[188:191], v[120:123]
	v_mfma_f32_16x16x32_bf16 v[116:119], v[152:155], v[196:199], v[116:119]
	v_mfma_f32_16x16x32_bf16 v[108:111], v[160:163], v[196:199], v[108:111]
	v_mfma_f32_16x16x32_bf16 v[100:103], v[152:155], v[204:207], v[100:103]
	v_mfma_f32_16x16x32_bf16 v[92:95], v[160:163], v[204:207], v[92:95]
	v_mfma_f32_16x16x32_bf16 v[84:87], v[152:155], v[212:215], v[84:87]
	v_mfma_f32_16x16x32_bf16 v[76:79], v[160:163], v[212:215], v[76:79]
	v_mfma_f32_16x16x32_bf16 v[124:127], v[156:159], v[192:195], v[124:127]
	v_mfma_f32_16x16x32_bf16 v[120:123], v[164:167], v[192:195], v[120:123]
	v_mfma_f32_16x16x32_bf16 v[116:119], v[156:159], v[200:203], v[116:119]
	v_mfma_f32_16x16x32_bf16 v[108:111], v[164:167], v[200:203], v[108:111]
	v_mfma_f32_16x16x32_bf16 v[100:103], v[156:159], v[208:211], v[100:103]
	v_mfma_f32_16x16x32_bf16 v[92:95], v[164:167], v[208:211], v[92:95]
	v_mfma_f32_16x16x32_bf16 v[84:87], v[156:159], v[216:219], v[84:87]
	v_mfma_f32_16x16x32_bf16 v[76:79], v[164:167], v[216:219], v[76:79]
	v_mfma_f32_16x16x32_bf16 v[112:115], v[168:171], v[188:191], v[112:115]
	v_mfma_f32_16x16x32_bf16 v[104:107], v[180:183], v[188:191], v[104:107]
	v_mfma_f32_16x16x32_bf16 v[96:99], v[168:171], v[196:199], v[96:99]
	v_mfma_f32_16x16x32_bf16 v[88:91], v[180:183], v[196:199], v[88:91]
	v_mfma_f32_16x16x32_bf16 v[80:83], v[168:171], v[204:207], v[80:83]
	v_mfma_f32_16x16x32_bf16 v[72:75], v[180:183], v[204:207], v[72:75]
	v_mfma_f32_16x16x32_bf16 v[68:71], v[168:171], v[212:215], v[68:71]
	v_mfma_f32_16x16x32_bf16 v[64:67], v[180:183], v[212:215], v[64:67]
	v_mfma_f32_16x16x32_bf16 v[112:115], v[172:175], v[192:195], v[112:115]
	v_mfma_f32_16x16x32_bf16 v[104:107], v[184:187], v[192:195], v[104:107]
	v_mfma_f32_16x16x32_bf16 v[96:99], v[172:175], v[200:203], v[96:99]
	v_mfma_f32_16x16x32_bf16 v[88:91], v[184:187], v[200:203], v[88:91]
	v_mfma_f32_16x16x32_bf16 v[80:83], v[172:175], v[208:211], v[80:83]
	v_mfma_f32_16x16x32_bf16 v[72:75], v[184:187], v[208:211], v[72:75]
	v_mfma_f32_16x16x32_bf16 v[68:71], v[172:175], v[216:219], v[68:71]
	v_mfma_f32_16x16x32_bf16 v[64:67], v[184:187], v[216:219], v[64:67]
	s_barrier
	s_setprio 1
	s_add_i32 s30, s86, s1
	s_mov_b32 m0, s30
	ds_read_b128 v[188:191], v151 offset:49152
	ds_read_b128 v[192:195], v151 offset:50176
	ds_read_b128 v[196:199], v151 offset:51200
	ds_read_b128 v[200:203], v151 offset:52224
	ds_read_b128 v[204:207], v151 offset:53248
	ds_read_b128 v[208:211], v151 offset:54272
	ds_read_b128 v[212:215], v151 offset:55296
	ds_read_b128 v[216:219], v151 offset:56320
	s_add_u32 s8, s68, 0x80
	s_addc_u32 s9, s69, 0
	global_load_lds_dwordx4 v130, s[8:9]
	s_add_i32 m0, s30, 0x2000
	s_add_u32 s30, s68, 0x80080
	s_addc_u32 s31, s69, 0
	s_add_i32 s68, s87, s1
	global_load_lds_dwordx4 v134, s[8:9]
	s_mov_b32 m0, s68
	s_nop 0
	global_load_lds_dwordx4 v130, s[30:31]
	s_add_i32 m0, s68, 0x2000
	s_nop 0
	global_load_lds_dwordx4 v134, s[30:31]
	s_mov_b32 m0, s72
	s_nop 0
	s_add_u32 s8, s70, 0x80
	s_addc_u32 s9, s71, 0
	global_load_lds_dwordx4 v128, s[8:9]
	s_mov_b32 m0, s73
	s_nop 0
	global_load_lds_dwordx4 v132, s[8:9]
	s_waitcnt vmcnt(8)
	s_waitcnt lgkmcnt(0)
	s_setprio 0
	s_barrier
	s_waitcnt lgkmcnt(0)
	v_mfma_f32_16x16x32_bf16 v[60:63], v[152:155], v[188:191], v[60:63]
	v_mfma_f32_16x16x32_bf16 v[56:59], v[160:163], v[188:191], v[56:59]
	v_mfma_f32_16x16x32_bf16 v[52:55], v[152:155], v[196:199], v[52:55]
	v_mfma_f32_16x16x32_bf16 v[44:47], v[160:163], v[196:199], v[44:47]
	v_mfma_f32_16x16x32_bf16 v[36:39], v[152:155], v[204:207], v[36:39]
	v_mfma_f32_16x16x32_bf16 v[28:31], v[160:163], v[204:207], v[28:31]
	v_mfma_f32_16x16x32_bf16 v[20:23], v[152:155], v[212:215], v[20:23]
	v_mfma_f32_16x16x32_bf16 v[12:15], v[160:163], v[212:215], v[12:15]
	v_mfma_f32_16x16x32_bf16 v[60:63], v[156:159], v[192:195], v[60:63]
	v_mfma_f32_16x16x32_bf16 v[56:59], v[164:167], v[192:195], v[56:59]
	v_mfma_f32_16x16x32_bf16 v[52:55], v[156:159], v[200:203], v[52:55]
	v_mfma_f32_16x16x32_bf16 v[44:47], v[164:167], v[200:203], v[44:47]
	v_mfma_f32_16x16x32_bf16 v[36:39], v[156:159], v[208:211], v[36:39]
	v_mfma_f32_16x16x32_bf16 v[28:31], v[164:167], v[208:211], v[28:31]
	v_mfma_f32_16x16x32_bf16 v[20:23], v[156:159], v[216:219], v[20:23]
	v_mfma_f32_16x16x32_bf16 v[12:15], v[164:167], v[216:219], v[12:15]
	v_mfma_f32_16x16x32_bf16 v[48:51], v[168:171], v[188:191], v[48:51]
	v_mfma_f32_16x16x32_bf16 v[40:43], v[180:183], v[188:191], v[40:43]
	v_mfma_f32_16x16x32_bf16 v[32:35], v[168:171], v[196:199], v[32:35]
	v_mfma_f32_16x16x32_bf16 v[24:27], v[180:183], v[196:199], v[24:27]
	v_mfma_f32_16x16x32_bf16 v[16:19], v[168:171], v[204:207], v[16:19]
	v_mfma_f32_16x16x32_bf16 v[8:11], v[180:183], v[204:207], v[8:11]
	v_mfma_f32_16x16x32_bf16 v[4:7], v[168:171], v[212:215], v[4:7]
	v_mfma_f32_16x16x32_bf16 v[0:3], v[180:183], v[212:215], v[0:3]
	v_mfma_f32_16x16x32_bf16 v[48:51], v[172:175], v[192:195], v[48:51]
	v_mfma_f32_16x16x32_bf16 v[40:43], v[184:187], v[192:195], v[40:43]
	v_mfma_f32_16x16x32_bf16 v[32:35], v[172:175], v[200:203], v[32:35]
	v_mfma_f32_16x16x32_bf16 v[24:27], v[184:187], v[200:203], v[24:27]
	v_mfma_f32_16x16x32_bf16 v[16:19], v[172:175], v[208:211], v[16:19]
	v_mfma_f32_16x16x32_bf16 v[8:11], v[184:187], v[208:211], v[8:11]
	v_mfma_f32_16x16x32_bf16 v[4:7], v[172:175], v[216:219], v[4:7]
	v_mfma_f32_16x16x32_bf16 v[0:3], v[184:187], v[216:219], v[0:3]
	s_barrier
; __device__ __forceinline__ unsigned cvt_pk_bf16(float lo, float hi) { unsigned r; asm volatile("v_cvt_pk_bf16_f32 %0, %1, %2" : "=v"(r) : "v"(lo), "v"(hi)); return r; }
; #define PG8_WAIT_V(n) asm volatile("s_waitcnt vmcnt(" #n ")" ::: "memory")
; #define PG8_BAR __builtin_amdgcn_s_barrier()
;     __device__ __forceinline__ void operator()(const f32x4 (&acc)[2][2][4][2], const Unit& u, int wr, int wc, int fr, int fq) const {
;         const int row0 = u.pm * BM + wr * 64 + fr; const int col0 = u.pn * BM + wc * 32 + 8 * fq;
; #pragma unroll
;         for (int ai = 0; ai < 2; ++ai)
; #pragma unroll
;             for (int m = 0; m < 4; ++m) { bf16_t* rowp = O + (size_t)(row0 + ai * HALF + m * 16) * ldc + col0;
; #pragma unroll
;                 for (int bj = 0; bj < 2; ++bj) { const f32x4 v0 = acc[ai][bj][m][0], v1 = acc[ai][bj][m][1];
;                     u32x4 w; w.x = cvt_pk_bf16(v0[0], v0[1]); w.y = cvt_pk_bf16(v0[2], v0[3]); w.z = cvt_pk_bf16(v1[0], v1[1]); w.w = cvt_pk_bf16(v1[2], v1[3]);
;                     *(u32x4*)(rowp + bj * HALF) = w; } }
; template <class Epi, class Sched, bool ALIGN_EPI = false, bool SP2 = false>
; __device__ __forceinline__ void gemm_phase(PG8_LAS unsigned char* lds, const Gemm g, const Sched& S, const Epi& E) {
;     ...
;         if constexpr (!Epi::AFTER_DRAIN) { E(acc, cur, wr, wc, fr, fq); S.done(cur); }
;         if (!has_next) break;
; #pragma unroll
;         for (int a = 0; a < 2; ++a)
; #pragma unroll
;             for (int b = 0; b < 2; ++b)
; #pragma unroll
;                 for (int m = 0; m < 4; ++m)
; #pragma unroll
;                     for (int n = 0; n < 2; ++n) acc[a][b][m][n] = (f32x4){0.f, 0.f, 0.f, 0.f};
;         cur = nxt; cA = nA; cB = nB; ++ui;
;         if constexpr (ALIGN_EPI) { if (wr == 1) PG8_BAR; }
;     }
;     PG8_WAIT_V(0);
;     if constexpr (!ALIGN_EPI) { if (wr == 0) PG8_BAR; }
	s_setprio 1
	s_add_i32 s85, s85, 2
	s_add_u32 s66, s66, 0x100
	s_addc_u32 s67, s67, 0
	s_add_u32 s83, s83, 0x100
	s_addc_u32 s84, s84, 0
	s_cmp_gt_u32 s85, 29
	s_cbranch_scc0 .LBB0_283
	v_lshl_add_u32 v152, s64, 8, v146
	v_lshl_or_b32 v144, s80, 8, v148
	v_ashrrev_i32_e32 v153, 31, v152
	v_ashrrev_i32_e32 v145, 31, v144
	v_lshlrev_b64 v[154:155], 12, v[152:153]
	v_lshl_add_u64 v[154:155], s[18:19], 0, v[154:155]
	v_lshlrev_b64 v[156:157], 1, v[144:145]
	v_lshl_add_u64 v[144:145], v[154:155], 0, v[156:157]
	v_cvt_pk_bf16_f32 v124, v124, v125
	v_cvt_pk_bf16_f32 v125, v126, v127
	v_cvt_pk_bf16_f32 v126, v120, v121
	v_cvt_pk_bf16_f32 v127, v122, v123
	global_store_dwordx4 v[144:145], v[124:127], off
	v_cvt_pk_bf16_f32 v112, v112, v113
	v_cvt_pk_bf16_f32 v113, v114, v115
	v_cvt_pk_bf16_f32 v114, v104, v105
	v_or_b32_e32 v104, 16, v152
	v_ashrrev_i32_e32 v105, 31, v104
	v_lshlrev_b64 v[104:105], 12, v[104:105]
	v_lshl_add_u64 v[104:105], s[18:19], 0, v[104:105]
	v_cvt_pk_bf16_f32 v115, v106, v107
	global_store_dwordx4 v[144:145], v[112:115], off offset:256
	s_mov_b32 s80, s56
	s_mov_b32 s64, s58
	v_lshl_add_u64 v[112:113], v[104:105], 0, v[156:157]
	v_cvt_pk_bf16_f32 v104, v116, v117
	v_cvt_pk_bf16_f32 v105, v118, v119
	v_cvt_pk_bf16_f32 v106, v108, v109
	v_cvt_pk_bf16_f32 v107, v110, v111
	global_store_dwordx4 v[112:113], v[104:107], off
	v_cvt_pk_bf16_f32 v96, v96, v97
	v_cvt_pk_bf16_f32 v97, v98, v99
	v_cvt_pk_bf16_f32 v98, v88, v89
	v_or_b32_e32 v88, 32, v152
	v_ashrrev_i32_e32 v89, 31, v88
	v_lshlrev_b64 v[88:89], 12, v[88:89]
	v_lshl_add_u64 v[88:89], s[18:19], 0, v[88:89]
	v_cvt_pk_bf16_f32 v99, v90, v91
	global_store_dwordx4 v[112:113], v[96:99], off offset:256
	s_mov_b64 s[68:69], s[62:63]
	s_mov_b64 s[66:67], s[60:61]
	v_lshl_add_u64 v[96:97], v[88:89], 0, v[156:157]
	v_cvt_pk_bf16_f32 v88, v100, v101
	v_cvt_pk_bf16_f32 v89, v102, v103
	v_cvt_pk_bf16_f32 v90, v92, v93
	v_cvt_pk_bf16_f32 v91, v94, v95
	global_store_dwordx4 v[96:97], v[88:91], off
	v_cvt_pk_bf16_f32 v80, v80, v81
	v_cvt_pk_bf16_f32 v81, v82, v83
	v_cvt_pk_bf16_f32 v82, v72, v73
	v_or_b32_e32 v72, 48, v152
	v_ashrrev_i32_e32 v73, 31, v72
	v_lshlrev_b64 v[72:73], 12, v[72:73]
	v_lshl_add_u64 v[72:73], s[18:19], 0, v[72:73]
	v_cvt_pk_bf16_f32 v83, v74, v75
	global_store_dwordx4 v[96:97], v[80:83], off offset:256
	s_nop 1
	v_lshl_add_u64 v[80:81], v[72:73], 0, v[156:157]
	v_cvt_pk_bf16_f32 v72, v84, v85
	v_cvt_pk_bf16_f32 v73, v86, v87
	v_cvt_pk_bf16_f32 v74, v76, v77
	v_cvt_pk_bf16_f32 v75, v78, v79
	global_store_dwordx4 v[80:81], v[72:75], off
	v_cvt_pk_bf16_f32 v68, v68, v69
	v_cvt_pk_bf16_f32 v69, v70, v71
	v_cvt_pk_bf16_f32 v70, v64, v65
	v_cvt_pk_bf16_f32 v71, v66, v67
	global_store_dwordx4 v[80:81], v[68:71], off offset:256
	v_cvt_pk_bf16_f32 v60, v60, v61
	v_cvt_pk_bf16_f32 v61, v62, v63
	v_cvt_pk_bf16_f32 v62, v56, v57
	v_add_co_u32_e32 v56, vcc, s76, v144
	v_lshl_add_u64 v[64:65], v[144:145], 0, s[6:7]
	s_nop 0
	v_addc_co_u32_e32 v57, vcc, 0, v145, vcc
	v_cvt_pk_bf16_f32 v63, v58, v59
	global_store_dwordx4 v[56:57], v[60:63], off
	v_cvt_pk_bf16_f32 v48, v48, v49
	v_cvt_pk_bf16_f32 v49, v50, v51
	v_cvt_pk_bf16_f32 v50, v40, v41
	v_cvt_pk_bf16_f32 v51, v42, v43
	global_store_dwordx4 v[64:65], v[48:51], off offset:256
	v_cvt_pk_bf16_f32 v40, v52, v53
	v_cvt_pk_bf16_f32 v41, v54, v55
	v_cvt_pk_bf16_f32 v42, v44, v45
	v_add_co_u32_e32 v44, vcc, s77, v144
	s_nop 0
	v_lshl_add_u64 v[48:49], v[144:145], 0, s[10:11]
	v_addc_co_u32_e32 v45, vcc, 0, v145, vcc
	v_cvt_pk_bf16_f32 v43, v46, v47
	global_store_dwordx4 v[44:45], v[40:43], off
	v_cvt_pk_bf16_f32 v32, v32, v33
	v_cvt_pk_bf16_f32 v33, v34, v35
	v_cvt_pk_bf16_f32 v34, v24, v25
	v_cvt_pk_bf16_f32 v35, v26, v27
	global_store_dwordx4 v[48:49], v[32:35], off offset:256
	v_cvt_pk_bf16_f32 v24, v36, v37
	v_cvt_pk_bf16_f32 v25, v38, v39
	v_cvt_pk_bf16_f32 v26, v28, v29
	v_add_co_u32_e32 v28, vcc, s78, v144
	s_nop 0
	v_lshl_add_u64 v[32:33], v[144:145], 0, s[36:37]
	v_addc_co_u32_e32 v29, vcc, 0, v145, vcc
	v_cvt_pk_bf16_f32 v27, v30, v31
	global_store_dwordx4 v[28:29], v[24:27], off
	v_cvt_pk_bf16_f32 v16, v16, v17
	v_cvt_pk_bf16_f32 v17, v18, v19
	v_cvt_pk_bf16_f32 v18, v8, v9
	v_cvt_pk_bf16_f32 v19, v10, v11
	global_store_dwordx4 v[32:33], v[16:19], off offset:256
	v_cvt_pk_bf16_f32 v8, v20, v21
	v_cvt_pk_bf16_f32 v9, v22, v23
	v_cvt_pk_bf16_f32 v10, v12, v13
	v_add_co_u32_e32 v12, vcc, s79, v144
	s_nop 0
	v_lshl_add_u64 v[16:17], v[144:145], 0, s[54:55]
	v_addc_co_u32_e32 v13, vcc, 0, v145, vcc
	s_and_b64 vcc, exec, s[4:5]
	v_cvt_pk_bf16_f32 v11, v14, v15
	global_store_dwordx4 v[12:13], v[8:11], off
	v_cvt_pk_bf16_f32 v4, v4, v5
	v_cvt_pk_bf16_f32 v5, v6, v7
	v_cvt_pk_bf16_f32 v6, v0, v1
	v_cvt_pk_bf16_f32 v7, v2, v3
	global_store_dwordx4 v[16:17], v[4:7], off offset:256
	s_cbranch_vccz .LBB0_276
	s_waitcnt vmcnt(0)
	s_cmpk_gt_u32 s0, 0xff
	s_cbranch_scc1 .LBB0_287
	s_barrier

; #define PG8_STAGE(bufoff, gbase, voff) do { _Pragma("unroll") for (int _i = 0; _i < 2; ++_i) \
;         __builtin_amdgcn_global_load_lds((const unsigned*)((const char*)(gbase) + (voff)[_i]), (PG8_LAS unsigned*)(lds + (bufoff) + ldsw + _i * 8192), 16, 0, 0); } while (0)
; #define PG8_LDA(dst, b, h) do { _Pragma("unroll") for (int m = 0; m < 4; ++m) _Pragma("unroll") for (int k = 0; k < 2; ++k) dst[m][k] = *(const PG8_LAS bf16x8*)(lds + PG8_SA(b, h) + aoff + m * 2048 + k * 1024); } while (0)
; #define PG8_LDB(dst, b, h) do { _Pragma("unroll") for (int n = 0; n < 2; ++n) _Pragma("unroll") for (int k = 0; k < 2; ++k) dst[n][k] = *(const PG8_LAS bf16x8*)(lds + PG8_SB(b, h) + boff + n * 2048 + k * 1024); } while (0)
; #define PG8_MMA(ai, bj, At, Bt) do { __builtin_amdgcn_s_setprio(1); _Pragma("unroll") for (int m = 0; m < 4; ++m) _Pragma("unroll") for (int n = 0; n < 2; ++n) _Pragma("unroll") for (int k = 0; k < 2; ++k) \
;         acc[ai][bj][m][n] = __builtin_amdgcn_mfma_f32_16x16x32_bf16(Bt[n][k], At[m][k], acc[ai][bj][m][n], 0, 0, 0); __builtin_amdgcn_s_setprio(0); } while (0)
; #define PG8_WAIT_V(n) asm volatile("s_waitcnt vmcnt(" #n ")" ::: "memory")
; #define PG8_WAIT_L(n) asm volatile("s_waitcnt lgkmcnt(" #n ")" ::: "memory")
; template <class Epi, class Sched, bool ALIGN_EPI = false, bool SP2 = false>
; __device__ __forceinline__ void gemm_phase(PG8_LAS unsigned char* lds, const Gemm g, const Sched& S, const Epi& E) {
;     ...
;             const bool last = (t == nt - 2);
;             const char* a1 = cA + (size_t)(t + 1) * kstep;
;             const char* a2 = last ? nA : cA + (size_t)(t + 2) * kstep; const char* b2 = last ? nB : cB + (size_t)(t + 2) * kstep;
;             const char* a3 = a2 + kstep; const char* b3 = b2 + kstep;
;             if (last && has_next) S.a_ready(nxt);
;             if constexpr (SP2) {
;             PG8_LDB(B0, 0, 0); PG8_LDB(B1, 0, 1); PG8_SCHED; PG8_LDA(At, 0, 0); PG8_STAGE(PG8_SA(1, 1), a1 + hstep, voffA);
;             PG8_WAIT_V(8); PG8_WAIT_L(0); PG8_BAR; PG8_MMA(0, 0, At, B0); PG8_MMA(0, 1, At, B1); PG8_BAR; PG8_SCHED;
;             PG8_LDA(At, 0, 1); PG8_STAGE(PG8_SB(0, 0), b2, voffB); PG8_STAGE(PG8_SB(0, 1), b2 + hstep, voffB); PG8_STAGE(PG8_SA(0, 0), a2, voffA);
;             PG8_WAIT_V(8); PG8_WAIT_L(0); PG8_BAR; PG8_MMA(1, 0, At, B0); PG8_MMA(1, 1, At, B1); PG8_BAR; PG8_SCHED;
.LBB0_404:
	ds_read_b128 v[118:121], v217
	ds_read_b128 v[126:129], v217 offset:1024
	ds_read_b128 v[130:133], v217 offset:2048
	ds_read_b128 v[134:137], v217 offset:3072
	ds_read_b128 v[138:141], v218
	ds_read_b128 v[142:145], v218 offset:1024
	ds_read_b128 v[146:149], v218 offset:2048
	ds_read_b128 v[150:153], v218 offset:3072
	s_add_u32 s30, s10, 0xfff80080
	s_addc_u32 s31, s11, -1
	s_cmp_eq_u32 s65, 28
	s_cselect_b32 s75, s1, s31
	s_cselect_b32 s74, s22, s30
	s_cselect_b32 s73, s33, s63
	s_cselect_b32 s72, s46, s47
	s_add_i32 m0, s77, 0xc000
	ds_read_b128 v[154:157], v219
	ds_read_b128 v[166:169], v219 offset:1024
	ds_read_b128 v[170:173], v219 offset:2048
	ds_read_b128 v[174:177], v219 offset:3072
	ds_read_b128 v[204:207], v219 offset:4096
	ds_read_b128 v[208:211], v219 offset:5120
	ds_read_b128 v[226:229], v219 offset:6144
	ds_read_b128 v[230:233], v219 offset:7168
	global_load_lds_dwordx4 v196, s[10:11]
	s_add_i32 m0, s77, 0xe000
	s_nop 0
	global_load_lds_dwordx4 v198, s[10:11]
	s_waitcnt vmcnt(8)
	s_waitcnt lgkmcnt(0)
	s_setprio 0
	s_barrier
	s_waitcnt lgkmcnt(0)
	v_mfma_f32_16x16x32_bf16 v[162:165], v[118:121], v[154:157], v[162:165]
	v_mfma_f32_16x16x32_bf16 v[60:63], v[130:133], v[154:157], v[60:63]
	v_mfma_f32_16x16x32_bf16 v[122:125], v[118:121], v[170:173], v[122:125]
	v_mfma_f32_16x16x32_bf16 v[52:55], v[130:133], v[170:173], v[52:55]
	v_mfma_f32_16x16x32_bf16 v[108:111], v[118:121], v[204:207], v[108:111]
	v_mfma_f32_16x16x32_bf16 v[44:47], v[130:133], v[204:207], v[44:47]
	v_mfma_f32_16x16x32_bf16 v[104:107], v[118:121], v[226:229], v[104:107]
	v_mfma_f32_16x16x32_bf16 v[40:43], v[130:133], v[226:229], v[40:43]
	v_mfma_f32_16x16x32_bf16 v[162:165], v[126:129], v[166:169], v[162:165]
	v_mfma_f32_16x16x32_bf16 v[60:63], v[134:137], v[166:169], v[60:63]
	v_mfma_f32_16x16x32_bf16 v[122:125], v[126:129], v[174:177], v[122:125]
	v_mfma_f32_16x16x32_bf16 v[52:55], v[134:137], v[174:177], v[52:55]
	v_mfma_f32_16x16x32_bf16 v[108:111], v[126:129], v[208:211], v[108:111]
	v_mfma_f32_16x16x32_bf16 v[44:47], v[134:137], v[208:211], v[44:47]
	v_mfma_f32_16x16x32_bf16 v[104:107], v[126:129], v[230:233], v[104:107]
	v_mfma_f32_16x16x32_bf16 v[40:43], v[134:137], v[230:233], v[40:43]
	v_mfma_f32_16x16x32_bf16 v[158:161], v[138:141], v[154:157], v[158:161]
	v_mfma_f32_16x16x32_bf16 v[56:59], v[146:149], v[154:157], v[56:59]
	v_mfma_f32_16x16x32_bf16 v[112:115], v[138:141], v[170:173], v[114:117]
	v_mfma_f32_16x16x32_bf16 v[48:51], v[146:149], v[170:173], v[48:51]
	v_mfma_f32_16x16x32_bf16 v[100:103], v[138:141], v[204:207], v[100:103]
	v_mfma_f32_16x16x32_bf16 v[36:39], v[146:149], v[204:207], v[36:39]
	v_mfma_f32_16x16x32_bf16 v[96:99], v[138:141], v[226:229], v[96:99]
	v_mfma_f32_16x16x32_bf16 v[32:35], v[146:149], v[226:229], v[32:35]
	v_mfma_f32_16x16x32_bf16 v[158:161], v[142:145], v[166:169], v[158:161]
	v_mfma_f32_16x16x32_bf16 v[56:59], v[150:153], v[166:169], v[56:59]
	v_mfma_f32_16x16x32_bf16 v[112:115], v[142:145], v[174:177], v[112:115]
	v_mfma_f32_16x16x32_bf16 v[48:51], v[150:153], v[174:177], v[48:51]
	v_mfma_f32_16x16x32_bf16 v[100:103], v[142:145], v[208:211], v[100:103]
	v_mfma_f32_16x16x32_bf16 v[36:39], v[150:153], v[208:211], v[36:39]
	v_mfma_f32_16x16x32_bf16 v[96:99], v[142:145], v[230:233], v[96:99]
	v_mfma_f32_16x16x32_bf16 v[32:35], v[150:153], v[230:233], v[32:35]
	s_barrier
	s_setprio 1
	s_add_i32 s30, s85, s29
	s_mov_b32 m0, s30
	ds_read_b128 v[154:157], v219 offset:16384
	ds_read_b128 v[166:169], v219 offset:17408
	ds_read_b128 v[170:173], v219 offset:18432
	ds_read_b128 v[174:177], v219 offset:19456
	ds_read_b128 v[204:207], v219 offset:20480
	ds_read_b128 v[208:211], v219 offset:21504
	ds_read_b128 v[226:229], v219 offset:22528
	ds_read_b128 v[230:233], v219 offset:23552
	global_load_lds_dwordx4 v184, s[72:73]
	s_add_i32 m0, s30, 0x2000
	s_add_u32 s30, s72, 0x80000
	s_addc_u32 s31, s73, 0
	s_add_i32 s71, s86, s29
	global_load_lds_dwordx4 v180, s[72:73]
	s_mov_b32 m0, s71
	s_nop 0
	global_load_lds_dwordx4 v184, s[30:31]
	s_add_i32 m0, s71, 0x2000
	s_nop 0
	global_load_lds_dwordx4 v180, s[30:31]
	s_mov_b32 m0, s77
	s_nop 0
	global_load_lds_dwordx4 v186, s[74:75]
	s_mov_b32 m0, s78
	s_nop 0
	global_load_lds_dwordx4 v182, s[74:75]
	s_waitcnt vmcnt(8)
	s_waitcnt lgkmcnt(0)
	s_setprio 0
	s_barrier
	s_waitcnt lgkmcnt(0)
	v_mfma_f32_16x16x32_bf16 v[92:95], v[118:121], v[154:157], v[92:95]
	v_mfma_f32_16x16x32_bf16 v[28:31], v[130:133], v[154:157], v[28:31]
	v_mfma_f32_16x16x32_bf16 v[84:87], v[118:121], v[170:173], v[84:87]
	v_mfma_f32_16x16x32_bf16 v[20:23], v[130:133], v[170:173], v[20:23]
	v_mfma_f32_16x16x32_bf16 v[76:79], v[118:121], v[204:207], v[76:79]
	v_mfma_f32_16x16x32_bf16 v[12:15], v[130:133], v[204:207], v[12:15]
	v_mfma_f32_16x16x32_bf16 v[72:75], v[118:121], v[226:229], v[72:75]
	v_mfma_f32_16x16x32_bf16 v[8:11], v[130:133], v[226:229], v[8:11]
	v_mfma_f32_16x16x32_bf16 v[92:95], v[126:129], v[166:169], v[92:95]
	v_mfma_f32_16x16x32_bf16 v[28:31], v[134:137], v[166:169], v[28:31]
	v_mfma_f32_16x16x32_bf16 v[84:87], v[126:129], v[174:177], v[84:87]
	v_mfma_f32_16x16x32_bf16 v[20:23], v[134:137], v[174:177], v[20:23]
	v_mfma_f32_16x16x32_bf16 v[76:79], v[126:129], v[208:211], v[76:79]
	v_mfma_f32_16x16x32_bf16 v[12:15], v[134:137], v[208:211], v[12:15]
	v_mfma_f32_16x16x32_bf16 v[72:75], v[126:129], v[230:233], v[72:75]
	v_mfma_f32_16x16x32_bf16 v[8:11], v[134:137], v[230:233], v[8:11]
	v_mfma_f32_16x16x32_bf16 v[88:91], v[138:141], v[154:157], v[88:91]
	v_mfma_f32_16x16x32_bf16 v[24:27], v[146:149], v[154:157], v[24:27]
	v_mfma_f32_16x16x32_bf16 v[80:83], v[138:141], v[170:173], v[80:83]
	v_mfma_f32_16x16x32_bf16 v[16:19], v[146:149], v[170:173], v[16:19]
	v_mfma_f32_16x16x32_bf16 v[68:71], v[138:141], v[204:207], v[68:71]
	v_mfma_f32_16x16x32_bf16 v[4:7], v[146:149], v[204:207], v[4:7]
	v_mfma_f32_16x16x32_bf16 v[64:67], v[138:141], v[226:229], v[64:67]
	v_mfma_f32_16x16x32_bf16 v[0:3], v[146:149], v[226:229], v[0:3]
	v_mfma_f32_16x16x32_bf16 v[88:91], v[142:145], v[166:169], v[88:91]
	v_mfma_f32_16x16x32_bf16 v[24:27], v[150:153], v[166:169], v[24:27]
	v_mfma_f32_16x16x32_bf16 v[80:83], v[142:145], v[174:177], v[80:83]
	v_mfma_f32_16x16x32_bf16 v[16:19], v[150:153], v[174:177], v[16:19]
	v_mfma_f32_16x16x32_bf16 v[68:71], v[142:145], v[208:211], v[68:71]
	v_mfma_f32_16x16x32_bf16 v[4:7], v[150:153], v[208:211], v[4:7]
	v_mfma_f32_16x16x32_bf16 v[64:67], v[142:145], v[230:233], v[64:67]
	v_mfma_f32_16x16x32_bf16 v[0:3], v[150:153], v[230:233], v[0:3]
	s_barrier
; #define PG8_STAGE(bufoff, gbase, voff) do { _Pragma("unroll") for (int _i = 0; _i < 2; ++_i) \
;         __builtin_amdgcn_global_load_lds((const unsigned*)((const char*)(gbase) + (voff)[_i]), (PG8_LAS unsigned*)(lds + (bufoff) + ldsw + _i * 8192), 16, 0, 0); } while (0)
; #define PG8_LDA(dst, b, h) do { _Pragma("unroll") for (int m = 0; m < 4; ++m) _Pragma("unroll") for (int k = 0; k < 2; ++k) dst[m][k] = *(const PG8_LAS bf16x8*)(lds + PG8_SA(b, h) + aoff + m * 2048 + k * 1024); } while (0)
; #define PG8_LDB(dst, b, h) do { _Pragma("unroll") for (int n = 0; n < 2; ++n) _Pragma("unroll") for (int k = 0; k < 2; ++k) dst[n][k] = *(const PG8_LAS bf16x8*)(lds + PG8_SB(b, h) + boff + n * 2048 + k * 1024); } while (0)
; #define PG8_MMA(ai, bj, At, Bt) do { __builtin_amdgcn_s_setprio(1); _Pragma("unroll") for (int m = 0; m < 4; ++m) _Pragma("unroll") for (int n = 0; n < 2; ++n) _Pragma("unroll") for (int k = 0; k < 2; ++k) \
;         acc[ai][bj][m][n] = __builtin_amdgcn_mfma_f32_16x16x32_bf16(Bt[n][k], At[m][k], acc[ai][bj][m][n], 0, 0, 0); __builtin_amdgcn_s_setprio(0); } while (0)
; #define PG8_WAIT_V(n) asm volatile("s_waitcnt vmcnt(" #n ")" ::: "memory")
; #define PG8_WAIT_L(n) asm volatile("s_waitcnt lgkmcnt(" #n ")" ::: "memory")
; #define PG8_BAR __builtin_amdgcn_s_barrier()
; #define PG8_SCHED __builtin_amdgcn_sched_barrier(0)
; template <class Epi, class Sched, bool ALIGN_EPI = false, bool SP2 = false>
; __device__ __forceinline__ void gemm_phase(PG8_LAS unsigned char* lds, const Gemm g, const Sched& S, const Epi& E) {
;     ...
;         for (int t = 0; t < nt; t += 2) {
;             const bool last = (t == nt - 2);
;             const char* a1 = cA + (size_t)(t + 1) * kstep;
;             const char* a2 = last ? nA : cA + (size_t)(t + 2) * kstep; const char* b2 = last ? nB : cB + (size_t)(t + 2) * kstep;
;     ...
;             PG8_LDB(B0, 1, 0); PG8_LDB(B1, 1, 1); PG8_SCHED; PG8_LDA(At, 1, 0); PG8_STAGE(PG8_SA(0, 1), a2 + hstep, voffA);
;             PG8_WAIT_V(8); PG8_WAIT_L(0); PG8_BAR; PG8_MMA(0, 0, At, B0); PG8_MMA(0, 1, At, B1); PG8_BAR; PG8_SCHED;
;             PG8_LDA(At, 1, 1); PG8_STAGE(PG8_SB(1, 0), b3, voffB); PG8_STAGE(PG8_SB(1, 1), b3 + hstep, voffB); PG8_STAGE(PG8_SA(1, 0), a3, voffA);
;             PG8_WAIT_V(8); PG8_WAIT_L(0); PG8_BAR; PG8_MMA(1, 0, At, B0); PG8_MMA(1, 1, At, B1); PG8_BAR; PG8_SCHED;
	s_setprio 1
	s_add_i32 s71, 0, 0x18000
	v_add_u32_e32 v116, s71, v213
	s_add_i32 s88, 0, 0x1c000
	ds_read_b128 v[118:121], v116
	ds_read_b128 v[126:129], v116 offset:1024
	ds_read_b128 v[130:133], v116 offset:2048
	ds_read_b128 v[134:137], v116 offset:3072
	v_add_u32_e32 v116, s88, v213
	ds_read_b128 v[138:141], v116
	ds_read_b128 v[142:145], v116 offset:1024
	ds_read_b128 v[146:149], v116 offset:2048
	ds_read_b128 v[150:153], v116 offset:3072
	s_add_u32 s30, s74, 0x80000
	s_addc_u32 s31, s75, 0
	s_mov_b32 m0, s79
	ds_read_b128 v[154:157], v219 offset:32768
	ds_read_b128 v[166:169], v219 offset:33792
	ds_read_b128 v[170:173], v219 offset:34816
	ds_read_b128 v[174:177], v219 offset:35840
	ds_read_b128 v[204:207], v219 offset:36864
	ds_read_b128 v[208:211], v219 offset:37888
	ds_read_b128 v[226:229], v219 offset:38912
	ds_read_b128 v[230:233], v219 offset:39936
	global_load_lds_dwordx4 v186, s[30:31]
	s_mov_b32 m0, s80
	s_nop 0
	global_load_lds_dwordx4 v182, s[30:31]
	s_waitcnt vmcnt(8)
	s_waitcnt lgkmcnt(0)
	s_setprio 0
	s_barrier
	s_waitcnt lgkmcnt(0)
	v_mfma_f32_16x16x32_bf16 v[162:165], v[118:121], v[154:157], v[162:165]
	v_mfma_f32_16x16x32_bf16 v[60:63], v[130:133], v[154:157], v[60:63]
	v_mfma_f32_16x16x32_bf16 v[122:125], v[118:121], v[170:173], v[122:125]
	v_mfma_f32_16x16x32_bf16 v[52:55], v[130:133], v[170:173], v[52:55]
	v_mfma_f32_16x16x32_bf16 v[108:111], v[118:121], v[204:207], v[108:111]
	v_mfma_f32_16x16x32_bf16 v[44:47], v[130:133], v[204:207], v[44:47]
	v_mfma_f32_16x16x32_bf16 v[104:107], v[118:121], v[226:229], v[104:107]
	v_mfma_f32_16x16x32_bf16 v[40:43], v[130:133], v[226:229], v[40:43]
	v_mfma_f32_16x16x32_bf16 v[162:165], v[126:129], v[166:169], v[162:165]
	v_mfma_f32_16x16x32_bf16 v[60:63], v[134:137], v[166:169], v[60:63]
	v_mfma_f32_16x16x32_bf16 v[122:125], v[126:129], v[174:177], v[122:125]
	v_mfma_f32_16x16x32_bf16 v[52:55], v[134:137], v[174:177], v[52:55]
	v_mfma_f32_16x16x32_bf16 v[108:111], v[126:129], v[208:211], v[108:111]
	v_mfma_f32_16x16x32_bf16 v[44:47], v[134:137], v[208:211], v[44:47]
	v_mfma_f32_16x16x32_bf16 v[104:107], v[126:129], v[230:233], v[104:107]
	v_mfma_f32_16x16x32_bf16 v[40:43], v[134:137], v[230:233], v[40:43]
	v_mfma_f32_16x16x32_bf16 v[158:161], v[138:141], v[154:157], v[158:161]
	v_mfma_f32_16x16x32_bf16 v[56:59], v[146:149], v[154:157], v[56:59]
	v_mfma_f32_16x16x32_bf16 v[112:115], v[138:141], v[170:173], v[112:115]
	v_mfma_f32_16x16x32_bf16 v[48:51], v[146:149], v[170:173], v[48:51]
	v_mfma_f32_16x16x32_bf16 v[100:103], v[138:141], v[204:207], v[100:103]
	v_mfma_f32_16x16x32_bf16 v[36:39], v[146:149], v[204:207], v[36:39]
	v_mfma_f32_16x16x32_bf16 v[96:99], v[138:141], v[226:229], v[96:99]
	v_mfma_f32_16x16x32_bf16 v[32:35], v[146:149], v[226:229], v[32:35]
	v_mfma_f32_16x16x32_bf16 v[158:161], v[142:145], v[166:169], v[158:161]
	v_mfma_f32_16x16x32_bf16 v[56:59], v[150:153], v[166:169], v[56:59]
	v_mfma_f32_16x16x32_bf16 v[114:117], v[142:145], v[174:177], v[112:115]
	v_mfma_f32_16x16x32_bf16 v[48:51], v[150:153], v[174:177], v[48:51]
	v_mfma_f32_16x16x32_bf16 v[100:103], v[142:145], v[208:211], v[100:103]
	v_mfma_f32_16x16x32_bf16 v[36:39], v[150:153], v[208:211], v[36:39]
	v_mfma_f32_16x16x32_bf16 v[96:99], v[142:145], v[230:233], v[96:99]
	v_mfma_f32_16x16x32_bf16 v[32:35], v[150:153], v[230:233], v[32:35]
	s_barrier
	s_setprio 1
	s_add_i32 s30, s71, s29
	s_mov_b32 m0, s30
	ds_read_b128 v[154:157], v219 offset:49152
	ds_read_b128 v[166:169], v219 offset:50176
	ds_read_b128 v[170:173], v219 offset:51200
	ds_read_b128 v[174:177], v219 offset:52224
	ds_read_b128 v[204:207], v219 offset:53248
	ds_read_b128 v[208:211], v219 offset:54272
	ds_read_b128 v[226:229], v219 offset:55296
	ds_read_b128 v[230:233], v219 offset:56320
	s_add_u32 s52, s72, 0x80
	s_addc_u32 s53, s73, 0
	global_load_lds_dwordx4 v184, s[52:53]
	s_add_i32 m0, s30, 0x2000
	s_add_u32 s30, s72, 0x80080
	s_addc_u32 s31, s73, 0
	s_add_i32 s71, s88, s29
	global_load_lds_dwordx4 v180, s[52:53]
	s_mov_b32 m0, s71
	s_nop 0
	global_load_lds_dwordx4 v184, s[30:31]
	s_add_i32 m0, s71, 0x2000
	s_nop 0
	global_load_lds_dwordx4 v180, s[30:31]
	s_mov_b32 m0, s83
	s_nop 0
	s_add_u32 s52, s74, 0x80
	s_addc_u32 s53, s75, 0
	global_load_lds_dwordx4 v186, s[52:53]
	s_mov_b32 m0, s84
	s_nop 0
	global_load_lds_dwordx4 v182, s[52:53]
	s_waitcnt vmcnt(8)
	s_waitcnt lgkmcnt(0)
	s_setprio 0
	s_barrier
	s_waitcnt lgkmcnt(0)
	v_mfma_f32_16x16x32_bf16 v[92:95], v[118:121], v[154:157], v[92:95]
	v_mfma_f32_16x16x32_bf16 v[28:31], v[130:133], v[154:157], v[28:31]
	v_mfma_f32_16x16x32_bf16 v[84:87], v[118:121], v[170:173], v[84:87]
	v_mfma_f32_16x16x32_bf16 v[20:23], v[130:133], v[170:173], v[20:23]
	v_mfma_f32_16x16x32_bf16 v[76:79], v[118:121], v[204:207], v[76:79]
	v_mfma_f32_16x16x32_bf16 v[12:15], v[130:133], v[204:207], v[12:15]
	v_mfma_f32_16x16x32_bf16 v[72:75], v[118:121], v[226:229], v[72:75]
	v_mfma_f32_16x16x32_bf16 v[8:11], v[130:133], v[226:229], v[8:11]
	v_mfma_f32_16x16x32_bf16 v[92:95], v[126:129], v[166:169], v[92:95]
	v_mfma_f32_16x16x32_bf16 v[28:31], v[134:137], v[166:169], v[28:31]
	v_mfma_f32_16x16x32_bf16 v[84:87], v[126:129], v[174:177], v[84:87]
	v_mfma_f32_16x16x32_bf16 v[20:23], v[134:137], v[174:177], v[20:23]
	v_mfma_f32_16x16x32_bf16 v[76:79], v[126:129], v[208:211], v[76:79]
	v_mfma_f32_16x16x32_bf16 v[12:15], v[134:137], v[208:211], v[12:15]
	v_mfma_f32_16x16x32_bf16 v[72:75], v[126:129], v[230:233], v[72:75]
	v_mfma_f32_16x16x32_bf16 v[8:11], v[134:137], v[230:233], v[8:11]
	v_mfma_f32_16x16x32_bf16 v[88:91], v[138:141], v[154:157], v[88:91]
	v_mfma_f32_16x16x32_bf16 v[24:27], v[146:149], v[154:157], v[24:27]
	v_mfma_f32_16x16x32_bf16 v[80:83], v[138:141], v[170:173], v[80:83]
	v_mfma_f32_16x16x32_bf16 v[16:19], v[146:149], v[170:173], v[16:19]
	v_mfma_f32_16x16x32_bf16 v[68:71], v[138:141], v[204:207], v[68:71]
	v_mfma_f32_16x16x32_bf16 v[4:7], v[146:149], v[204:207], v[4:7]
	v_mfma_f32_16x16x32_bf16 v[64:67], v[138:141], v[226:229], v[64:67]
	v_mfma_f32_16x16x32_bf16 v[0:3], v[146:149], v[226:229], v[0:3]
	v_mfma_f32_16x16x32_bf16 v[88:91], v[142:145], v[166:169], v[88:91]
	v_mfma_f32_16x16x32_bf16 v[24:27], v[150:153], v[166:169], v[24:27]
	v_mfma_f32_16x16x32_bf16 v[80:83], v[142:145], v[174:177], v[80:83]
	v_mfma_f32_16x16x32_bf16 v[16:19], v[150:153], v[174:177], v[16:19]
	v_mfma_f32_16x16x32_bf16 v[68:71], v[142:145], v[208:211], v[68:71]
	v_mfma_f32_16x16x32_bf16 v[4:7], v[150:153], v[208:211], v[4:7]
	v_mfma_f32_16x16x32_bf16 v[64:67], v[142:145], v[230:233], v[64:67]
	v_mfma_f32_16x16x32_bf16 v[0:3], v[150:153], v[230:233], v[0:3]
	s_barrier
	s_setprio 1
	s_add_i32 s65, s65, 2
	s_add_u32 s10, s10, 0x100
	s_addc_u32 s11, s11, 0
	s_add_u32 s47, s47, 0x100
	s_addc_u32 s63, s63, 0
	s_cmp_gt_u32 s65, 29
	s_cbranch_scc0 .LBB0_404
	s_and_b64 vcc, exec, s[54:55]
	s_cbranch_vccz .LBB0_407
	s_barrier

; #define PG8_STAGE(bufoff, gbase, voff) do { _Pragma("unroll") for (int _i = 0; _i < 2; ++_i) \
;         __builtin_amdgcn_global_load_lds((const unsigned*)((const char*)(gbase) + (voff)[_i]), (PG8_LAS unsigned*)(lds + (bufoff) + ldsw + _i * 8192), 16, 0, 0); } while (0)
; #define PG8_LDA(dst, b, h) do { _Pragma("unroll") for (int m = 0; m < 4; ++m) _Pragma("unroll") for (int k = 0; k < 2; ++k) dst[m][k] = *(const PG8_LAS bf16x8*)(lds + PG8_SA(b, h) + aoff + m * 2048 + k * 1024); } while (0)
; #define PG8_LDB(dst, b, h) do { _Pragma("unroll") for (int n = 0; n < 2; ++n) _Pragma("unroll") for (int k = 0; k < 2; ++k) dst[n][k] = *(const PG8_LAS bf16x8*)(lds + PG8_SB(b, h) + boff + n * 2048 + k * 1024); } while (0)
; #define PG8_MMA(ai, bj, At, Bt) do { __builtin_amdgcn_s_setprio(1); _Pragma("unroll") for (int m = 0; m < 4; ++m) _Pragma("unroll") for (int n = 0; n < 2; ++n) _Pragma("unroll") for (int k = 0; k < 2; ++k) \
;         acc[ai][bj][m][n] = __builtin_amdgcn_mfma_f32_16x16x32_bf16(Bt[n][k], At[m][k], acc[ai][bj][m][n], 0, 0, 0); __builtin_amdgcn_s_setprio(0); } while (0)
; #define PG8_WAIT_V(n) asm volatile("s_waitcnt vmcnt(" #n ")" ::: "memory")
; #define PG8_WAIT_L(n) asm volatile("s_waitcnt lgkmcnt(" #n ")" ::: "memory")
; template <class Epi, class Sched, bool ALIGN_EPI = false, bool SP2 = false>
; __device__ __forceinline__ void gemm_phase(PG8_LAS unsigned char* lds, const Gemm g, const Sched& S, const Epi& E) {
;     ...
;             const bool last = (t == nt - 2);
;             const char* a1 = cA + (size_t)(t + 1) * kstep;
;             const char* a2 = last ? nA : cA + (size_t)(t + 2) * kstep; const char* b2 = last ? nB : cB + (size_t)(t + 2) * kstep;
;             const char* a3 = a2 + kstep; const char* b3 = b2 + kstep;
;             if (last && has_next) S.a_ready(nxt);
;             if constexpr (SP2) {
;             PG8_LDB(B0, 0, 0); PG8_LDB(B1, 0, 1); PG8_SCHED; PG8_LDA(At, 0, 0); PG8_STAGE(PG8_SA(1, 1), a1 + hstep, voffA);
;             PG8_WAIT_V(8); PG8_WAIT_L(0); PG8_BAR; PG8_MMA(0, 0, At, B0); PG8_MMA(0, 1, At, B1); PG8_BAR; PG8_SCHED;
;             PG8_LDA(At, 0, 1); PG8_STAGE(PG8_SB(0, 0), b2, voffB); PG8_STAGE(PG8_SB(0, 1), b2 + hstep, voffB); PG8_STAGE(PG8_SA(0, 0), a2, voffA);
;             PG8_WAIT_V(8); PG8_WAIT_L(0); PG8_BAR; PG8_MMA(1, 0, At, B0); PG8_MMA(1, 1, At, B1); PG8_BAR; PG8_SCHED;
.LBB0_552:
	ds_read_b128 v[152:155], v149
	ds_read_b128 v[156:159], v149 offset:1024
	ds_read_b128 v[160:163], v149 offset:2048
	ds_read_b128 v[164:167], v149 offset:3072
	ds_read_b128 v[168:171], v150
	ds_read_b128 v[172:175], v150 offset:1024
	ds_read_b128 v[180:183], v150 offset:2048
	ds_read_b128 v[184:187], v150 offset:3072
	s_add_u32 s34, s26, 0x100
	s_addc_u32 s35, s27, 0
	s_cmpk_eq_i32 s67, 0x54
	s_cselect_b32 s45, s7, s35
	s_cselect_b32 s44, s6, s34
	s_cselect_b32 s37, s9, s66
	s_cselect_b32 s36, s8, s65
	s_add_i32 m0, s29, 0xc000
	ds_read_b128 v[188:191], v151
	ds_read_b128 v[192:195], v151 offset:1024
	ds_read_b128 v[196:199], v151 offset:2048
	ds_read_b128 v[200:203], v151 offset:3072
	ds_read_b128 v[204:207], v151 offset:4096
	ds_read_b128 v[208:211], v151 offset:5120
	ds_read_b128 v[212:215], v151 offset:6144
	ds_read_b128 v[216:219], v151 offset:7168
	global_load_lds_dwordx4 v136, s[26:27]
	s_add_i32 m0, s29, 0xe000
	s_nop 0
	global_load_lds_dwordx4 v138, s[26:27]
	s_waitcnt vmcnt(8)
	s_waitcnt lgkmcnt(0)
	s_setprio 0
	s_barrier
	s_waitcnt lgkmcnt(0)
	v_mfma_f32_16x16x32_bf16 v[124:127], v[152:155], v[188:191], v[124:127]
	v_mfma_f32_16x16x32_bf16 v[120:123], v[160:163], v[188:191], v[120:123]
	v_mfma_f32_16x16x32_bf16 v[116:119], v[152:155], v[196:199], v[116:119]
	v_mfma_f32_16x16x32_bf16 v[108:111], v[160:163], v[196:199], v[108:111]
	v_mfma_f32_16x16x32_bf16 v[100:103], v[152:155], v[204:207], v[100:103]
	v_mfma_f32_16x16x32_bf16 v[92:95], v[160:163], v[204:207], v[92:95]
	v_mfma_f32_16x16x32_bf16 v[84:87], v[152:155], v[212:215], v[84:87]
	v_mfma_f32_16x16x32_bf16 v[76:79], v[160:163], v[212:215], v[76:79]
	v_mfma_f32_16x16x32_bf16 v[124:127], v[156:159], v[192:195], v[124:127]
	v_mfma_f32_16x16x32_bf16 v[120:123], v[164:167], v[192:195], v[120:123]
	v_mfma_f32_16x16x32_bf16 v[116:119], v[156:159], v[200:203], v[116:119]
	v_mfma_f32_16x16x32_bf16 v[108:111], v[164:167], v[200:203], v[108:111]
	v_mfma_f32_16x16x32_bf16 v[100:103], v[156:159], v[208:211], v[100:103]
	v_mfma_f32_16x16x32_bf16 v[92:95], v[164:167], v[208:211], v[92:95]
	v_mfma_f32_16x16x32_bf16 v[84:87], v[156:159], v[216:219], v[84:87]
	v_mfma_f32_16x16x32_bf16 v[76:79], v[164:167], v[216:219], v[76:79]
	v_mfma_f32_16x16x32_bf16 v[112:115], v[168:171], v[188:191], v[112:115]
	v_mfma_f32_16x16x32_bf16 v[104:107], v[180:183], v[188:191], v[104:107]
	v_mfma_f32_16x16x32_bf16 v[96:99], v[168:171], v[196:199], v[96:99]
	v_mfma_f32_16x16x32_bf16 v[88:91], v[180:183], v[196:199], v[88:91]
	v_mfma_f32_16x16x32_bf16 v[80:83], v[168:171], v[204:207], v[80:83]
	v_mfma_f32_16x16x32_bf16 v[72:75], v[180:183], v[204:207], v[72:75]
	v_mfma_f32_16x16x32_bf16 v[68:71], v[168:171], v[212:215], v[68:71]
	v_mfma_f32_16x16x32_bf16 v[64:67], v[180:183], v[212:215], v[64:67]
	v_mfma_f32_16x16x32_bf16 v[112:115], v[172:175], v[192:195], v[112:115]
	v_mfma_f32_16x16x32_bf16 v[104:107], v[184:187], v[192:195], v[104:107]
	v_mfma_f32_16x16x32_bf16 v[96:99], v[172:175], v[200:203], v[96:99]
	v_mfma_f32_16x16x32_bf16 v[88:91], v[184:187], v[200:203], v[88:91]
	v_mfma_f32_16x16x32_bf16 v[80:83], v[172:175], v[208:211], v[80:83]
	v_mfma_f32_16x16x32_bf16 v[72:75], v[184:187], v[208:211], v[72:75]
	v_mfma_f32_16x16x32_bf16 v[68:71], v[172:175], v[216:219], v[68:71]
	v_mfma_f32_16x16x32_bf16 v[64:67], v[184:187], v[216:219], v[64:67]
	s_barrier
	s_setprio 1
	s_add_i32 s26, s55, s1
	s_mov_b32 m0, s26
	ds_read_b128 v[188:191], v151 offset:16384
	ds_read_b128 v[192:195], v151 offset:17408
	ds_read_b128 v[196:199], v151 offset:18432
	ds_read_b128 v[200:203], v151 offset:19456
	ds_read_b128 v[204:207], v151 offset:20480
	ds_read_b128 v[208:211], v151 offset:21504
	ds_read_b128 v[212:215], v151 offset:22528
	ds_read_b128 v[216:219], v151 offset:23552
	global_load_lds_dwordx4 v130, s[36:37]
	s_add_i32 m0, s26, 0x2000
	s_add_u32 s26, s36, 0x160000
	s_addc_u32 s27, s37, 0
	s_add_i32 s30, s56, s1
	global_load_lds_dwordx4 v134, s[36:37]
	s_mov_b32 m0, s30
	s_nop 0
	global_load_lds_dwordx4 v130, s[26:27]
	s_add_i32 m0, s30, 0x2000
	s_nop 0
	global_load_lds_dwordx4 v134, s[26:27]
	s_mov_b32 m0, s29
	s_nop 0
	global_load_lds_dwordx4 v128, s[44:45]
	s_mov_b32 m0, s33
	s_nop 0
	global_load_lds_dwordx4 v132, s[44:45]
	s_waitcnt vmcnt(8)
	s_waitcnt lgkmcnt(0)
	s_setprio 0
	s_barrier
	s_waitcnt lgkmcnt(0)
	v_mfma_f32_16x16x32_bf16 v[60:63], v[152:155], v[188:191], v[60:63]
	v_mfma_f32_16x16x32_bf16 v[56:59], v[160:163], v[188:191], v[56:59]
	v_mfma_f32_16x16x32_bf16 v[52:55], v[152:155], v[196:199], v[52:55]
	v_mfma_f32_16x16x32_bf16 v[44:47], v[160:163], v[196:199], v[44:47]
	v_mfma_f32_16x16x32_bf16 v[36:39], v[152:155], v[204:207], v[36:39]
	v_mfma_f32_16x16x32_bf16 v[28:31], v[160:163], v[204:207], v[28:31]
	v_mfma_f32_16x16x32_bf16 v[20:23], v[152:155], v[212:215], v[20:23]
	v_mfma_f32_16x16x32_bf16 v[12:15], v[160:163], v[212:215], v[12:15]
	v_mfma_f32_16x16x32_bf16 v[60:63], v[156:159], v[192:195], v[60:63]
	v_mfma_f32_16x16x32_bf16 v[56:59], v[164:167], v[192:195], v[56:59]
	v_mfma_f32_16x16x32_bf16 v[52:55], v[156:159], v[200:203], v[52:55]
	v_mfma_f32_16x16x32_bf16 v[44:47], v[164:167], v[200:203], v[44:47]
	v_mfma_f32_16x16x32_bf16 v[36:39], v[156:159], v[208:211], v[36:39]
	v_mfma_f32_16x16x32_bf16 v[28:31], v[164:167], v[208:211], v[28:31]
	v_mfma_f32_16x16x32_bf16 v[20:23], v[156:159], v[216:219], v[20:23]
	v_mfma_f32_16x16x32_bf16 v[12:15], v[164:167], v[216:219], v[12:15]
	v_mfma_f32_16x16x32_bf16 v[48:51], v[168:171], v[188:191], v[48:51]
	v_mfma_f32_16x16x32_bf16 v[40:43], v[180:183], v[188:191], v[40:43]
	v_mfma_f32_16x16x32_bf16 v[32:35], v[168:171], v[196:199], v[32:35]
	v_mfma_f32_16x16x32_bf16 v[24:27], v[180:183], v[196:199], v[24:27]
	v_mfma_f32_16x16x32_bf16 v[16:19], v[168:171], v[204:207], v[16:19]
	v_mfma_f32_16x16x32_bf16 v[8:11], v[180:183], v[204:207], v[8:11]
	v_mfma_f32_16x16x32_bf16 v[4:7], v[168:171], v[212:215], v[4:7]
	v_mfma_f32_16x16x32_bf16 v[0:3], v[180:183], v[212:215], v[0:3]
	v_mfma_f32_16x16x32_bf16 v[48:51], v[172:175], v[192:195], v[48:51]
	v_mfma_f32_16x16x32_bf16 v[40:43], v[184:187], v[192:195], v[40:43]
	v_mfma_f32_16x16x32_bf16 v[32:35], v[172:175], v[200:203], v[32:35]
	v_mfma_f32_16x16x32_bf16 v[24:27], v[184:187], v[200:203], v[24:27]
	v_mfma_f32_16x16x32_bf16 v[16:19], v[172:175], v[208:211], v[16:19]
	v_mfma_f32_16x16x32_bf16 v[8:11], v[184:187], v[208:211], v[8:11]
	v_mfma_f32_16x16x32_bf16 v[4:7], v[172:175], v[216:219], v[4:7]
	v_mfma_f32_16x16x32_bf16 v[0:3], v[184:187], v[216:219], v[0:3]
	s_barrier
; #define PG8_STAGE(bufoff, gbase, voff) do { _Pragma("unroll") for (int _i = 0; _i < 2; ++_i) \
;         __builtin_amdgcn_global_load_lds((const unsigned*)((const char*)(gbase) + (voff)[_i]), (PG8_LAS unsigned*)(lds + (bufoff) + ldsw + _i * 8192), 16, 0, 0); } while (0)
; #define PG8_LDA(dst, b, h) do { _Pragma("unroll") for (int m = 0; m < 4; ++m) _Pragma("unroll") for (int k = 0; k < 2; ++k) dst[m][k] = *(const PG8_LAS bf16x8*)(lds + PG8_SA(b, h) + aoff + m * 2048 + k * 1024); } while (0)
; #define PG8_LDB(dst, b, h) do { _Pragma("unroll") for (int n = 0; n < 2; ++n) _Pragma("unroll") for (int k = 0; k < 2; ++k) dst[n][k] = *(const PG8_LAS bf16x8*)(lds + PG8_SB(b, h) + boff + n * 2048 + k * 1024); } while (0)
; #define PG8_MMA(ai, bj, At, Bt) do { __builtin_amdgcn_s_setprio(1); _Pragma("unroll") for (int m = 0; m < 4; ++m) _Pragma("unroll") for (int n = 0; n < 2; ++n) _Pragma("unroll") for (int k = 0; k < 2; ++k) \
;         acc[ai][bj][m][n] = __builtin_amdgcn_mfma_f32_16x16x32_bf16(Bt[n][k], At[m][k], acc[ai][bj][m][n], 0, 0, 0); __builtin_amdgcn_s_setprio(0); } while (0)
; #define PG8_WAIT_V(n) asm volatile("s_waitcnt vmcnt(" #n ")" ::: "memory")
; #define PG8_WAIT_L(n) asm volatile("s_waitcnt lgkmcnt(" #n ")" ::: "memory")
; #define PG8_BAR __builtin_amdgcn_s_barrier()
; #define PG8_SCHED __builtin_amdgcn_sched_barrier(0)
; template <class Epi, class Sched, bool ALIGN_EPI = false, bool SP2 = false>
; __device__ __forceinline__ void gemm_phase(PG8_LAS unsigned char* lds, const Gemm g, const Sched& S, const Epi& E) {
;     ...
;             PG8_LDB(B0, 1, 0); PG8_LDB(B1, 1, 1); PG8_SCHED; PG8_LDA(At, 1, 0); PG8_STAGE(PG8_SA(0, 1), a2 + hstep, voffA);
;             PG8_WAIT_V(8); PG8_WAIT_L(0); PG8_BAR; PG8_MMA(0, 0, At, B0); PG8_MMA(0, 1, At, B1); PG8_BAR; PG8_SCHED;
;             PG8_LDA(At, 1, 1); PG8_STAGE(PG8_SB(1, 0), b3, voffB); PG8_STAGE(PG8_SB(1, 1), b3 + hstep, voffB); PG8_STAGE(PG8_SA(1, 0), a3, voffA);
;             PG8_WAIT_V(8); PG8_WAIT_L(0); PG8_BAR; PG8_MMA(1, 0, At, B0); PG8_MMA(1, 1, At, B1); PG8_BAR; PG8_SCHED;
	s_setprio 1
	s_add_i32 s30, 0, 0x18000
	s_add_i32 s31, 0, 0x1c000
	v_add_u32_e32 v164, s30, v147
	v_add_u32_e32 v184, s31, v147
	ds_read_b128 v[152:155], v164
	ds_read_b128 v[156:159], v164 offset:1024
	ds_read_b128 v[160:163], v164 offset:2048
	ds_read_b128 v[164:167], v164 offset:3072
	ds_read_b128 v[168:171], v184
	ds_read_b128 v[172:175], v184 offset:1024
	ds_read_b128 v[180:183], v184 offset:2048
	ds_read_b128 v[184:187], v184 offset:3072
	s_add_u32 s26, s44, 0x160000
	s_addc_u32 s27, s45, 0
	s_mov_b32 m0, s46
	ds_read_b128 v[188:191], v151 offset:32768
	ds_read_b128 v[192:195], v151 offset:33792
	ds_read_b128 v[196:199], v151 offset:34816
	ds_read_b128 v[200:203], v151 offset:35840
	ds_read_b128 v[204:207], v151 offset:36864
	ds_read_b128 v[208:211], v151 offset:37888
	ds_read_b128 v[212:215], v151 offset:38912
	ds_read_b128 v[216:219], v151 offset:39936
	global_load_lds_dwordx4 v128, s[26:27]
	s_mov_b32 m0, s47
	s_nop 0
	global_load_lds_dwordx4 v132, s[26:27]
	s_waitcnt vmcnt(8)
	s_waitcnt lgkmcnt(0)
	s_setprio 0
	s_barrier
	s_waitcnt lgkmcnt(0)
	v_mfma_f32_16x16x32_bf16 v[124:127], v[152:155], v[188:191], v[124:127]
	v_mfma_f32_16x16x32_bf16 v[120:123], v[160:163], v[188:191], v[120:123]
	v_mfma_f32_16x16x32_bf16 v[116:119], v[152:155], v[196:199], v[116:119]
	v_mfma_f32_16x16x32_bf16 v[108:111], v[160:163], v[196:199], v[108:111]
	v_mfma_f32_16x16x32_bf16 v[100:103], v[152:155], v[204:207], v[100:103]
	v_mfma_f32_16x16x32_bf16 v[92:95], v[160:163], v[204:207], v[92:95]
	v_mfma_f32_16x16x32_bf16 v[84:87], v[152:155], v[212:215], v[84:87]
	v_mfma_f32_16x16x32_bf16 v[76:79], v[160:163], v[212:215], v[76:79]
	v_mfma_f32_16x16x32_bf16 v[124:127], v[156:159], v[192:195], v[124:127]
	v_mfma_f32_16x16x32_bf16 v[120:123], v[164:167], v[192:195], v[120:123]
	v_mfma_f32_16x16x32_bf16 v[116:119], v[156:159], v[200:203], v[116:119]
	v_mfma_f32_16x16x32_bf16 v[108:111], v[164:167], v[200:203], v[108:111]
	v_mfma_f32_16x16x32_bf16 v[100:103], v[156:159], v[208:211], v[100:103]
	v_mfma_f32_16x16x32_bf16 v[92:95], v[164:167], v[208:211], v[92:95]
	v_mfma_f32_16x16x32_bf16 v[84:87], v[156:159], v[216:219], v[84:87]
	v_mfma_f32_16x16x32_bf16 v[76:79], v[164:167], v[216:219], v[76:79]
	v_mfma_f32_16x16x32_bf16 v[112:115], v[168:171], v[188:191], v[112:115]
	v_mfma_f32_16x16x32_bf16 v[104:107], v[180:183], v[188:191], v[104:107]
	v_mfma_f32_16x16x32_bf16 v[96:99], v[168:171], v[196:199], v[96:99]
	v_mfma_f32_16x16x32_bf16 v[88:91], v[180:183], v[196:199], v[88:91]
	v_mfma_f32_16x16x32_bf16 v[80:83], v[168:171], v[204:207], v[80:83]
	v_mfma_f32_16x16x32_bf16 v[72:75], v[180:183], v[204:207], v[72:75]
	v_mfma_f32_16x16x32_bf16 v[68:71], v[168:171], v[212:215], v[68:71]
	v_mfma_f32_16x16x32_bf16 v[64:67], v[180:183], v[212:215], v[64:67]
	v_mfma_f32_16x16x32_bf16 v[112:115], v[172:175], v[192:195], v[112:115]
	v_mfma_f32_16x16x32_bf16 v[104:107], v[184:187], v[192:195], v[104:107]
	v_mfma_f32_16x16x32_bf16 v[96:99], v[172:175], v[200:203], v[96:99]
	v_mfma_f32_16x16x32_bf16 v[88:91], v[184:187], v[200:203], v[88:91]
	v_mfma_f32_16x16x32_bf16 v[80:83], v[172:175], v[208:211], v[80:83]
	v_mfma_f32_16x16x32_bf16 v[72:75], v[184:187], v[208:211], v[72:75]
	v_mfma_f32_16x16x32_bf16 v[68:71], v[172:175], v[216:219], v[68:71]
	v_mfma_f32_16x16x32_bf16 v[64:67], v[184:187], v[216:219], v[64:67]
	s_barrier
	s_setprio 1
	s_add_i32 s26, s30, s1
	s_mov_b32 m0, s26
	ds_read_b128 v[188:191], v151 offset:49152
	ds_read_b128 v[192:195], v151 offset:50176
	ds_read_b128 v[196:199], v151 offset:51200
	ds_read_b128 v[200:203], v151 offset:52224
	ds_read_b128 v[204:207], v151 offset:53248
	ds_read_b128 v[208:211], v151 offset:54272
	ds_read_b128 v[212:215], v151 offset:55296
	ds_read_b128 v[216:219], v151 offset:56320
	s_add_u32 s10, s36, 0x80
	s_addc_u32 s11, s37, 0
	global_load_lds_dwordx4 v130, s[10:11]
	s_add_i32 m0, s26, 0x2000
	s_add_u32 s26, s36, 0x160080
	s_addc_u32 s27, s37, 0
	s_add_i32 s30, s31, s1
	global_load_lds_dwordx4 v134, s[10:11]
	s_mov_b32 m0, s30
	s_nop 0
	global_load_lds_dwordx4 v130, s[26:27]
	s_add_i32 m0, s30, 0x2000
	s_nop 0
	global_load_lds_dwordx4 v134, s[26:27]
	s_mov_b32 m0, s53
	s_nop 0
	s_add_u32 s10, s44, 0x80
	s_addc_u32 s11, s45, 0
	global_load_lds_dwordx4 v128, s[10:11]
	s_mov_b32 m0, s54
	s_nop 0
	global_load_lds_dwordx4 v132, s[10:11]
	s_waitcnt vmcnt(8)
	s_waitcnt lgkmcnt(0)
	s_setprio 0
	s_barrier
	s_waitcnt lgkmcnt(0)
	v_mfma_f32_16x16x32_bf16 v[60:63], v[152:155], v[188:191], v[60:63]
	v_mfma_f32_16x16x32_bf16 v[56:59], v[160:163], v[188:191], v[56:59]
	v_mfma_f32_16x16x32_bf16 v[52:55], v[152:155], v[196:199], v[52:55]
	v_mfma_f32_16x16x32_bf16 v[44:47], v[160:163], v[196:199], v[44:47]
	v_mfma_f32_16x16x32_bf16 v[36:39], v[152:155], v[204:207], v[36:39]
	v_mfma_f32_16x16x32_bf16 v[28:31], v[160:163], v[204:207], v[28:31]
	v_mfma_f32_16x16x32_bf16 v[20:23], v[152:155], v[212:215], v[20:23]
	v_mfma_f32_16x16x32_bf16 v[12:15], v[160:163], v[212:215], v[12:15]
	v_mfma_f32_16x16x32_bf16 v[60:63], v[156:159], v[192:195], v[60:63]
	v_mfma_f32_16x16x32_bf16 v[56:59], v[164:167], v[192:195], v[56:59]
	v_mfma_f32_16x16x32_bf16 v[52:55], v[156:159], v[200:203], v[52:55]
	v_mfma_f32_16x16x32_bf16 v[44:47], v[164:167], v[200:203], v[44:47]
	v_mfma_f32_16x16x32_bf16 v[36:39], v[156:159], v[208:211], v[36:39]
	v_mfma_f32_16x16x32_bf16 v[28:31], v[164:167], v[208:211], v[28:31]
	v_mfma_f32_16x16x32_bf16 v[20:23], v[156:159], v[216:219], v[20:23]
	v_mfma_f32_16x16x32_bf16 v[12:15], v[164:167], v[216:219], v[12:15]
	v_mfma_f32_16x16x32_bf16 v[48:51], v[168:171], v[188:191], v[48:51]
	v_mfma_f32_16x16x32_bf16 v[40:43], v[180:183], v[188:191], v[40:43]
	v_mfma_f32_16x16x32_bf16 v[32:35], v[168:171], v[196:199], v[32:35]
	v_mfma_f32_16x16x32_bf16 v[24:27], v[180:183], v[196:199], v[24:27]
	v_mfma_f32_16x16x32_bf16 v[16:19], v[168:171], v[204:207], v[16:19]
	v_mfma_f32_16x16x32_bf16 v[8:11], v[180:183], v[204:207], v[8:11]
	v_mfma_f32_16x16x32_bf16 v[4:7], v[168:171], v[212:215], v[4:7]
	v_mfma_f32_16x16x32_bf16 v[0:3], v[180:183], v[212:215], v[0:3]
	v_mfma_f32_16x16x32_bf16 v[48:51], v[172:175], v[192:195], v[48:51]
	v_mfma_f32_16x16x32_bf16 v[40:43], v[184:187], v[192:195], v[40:43]
	v_mfma_f32_16x16x32_bf16 v[32:35], v[172:175], v[200:203], v[32:35]
	v_mfma_f32_16x16x32_bf16 v[24:27], v[184:187], v[200:203], v[24:27]
	v_mfma_f32_16x16x32_bf16 v[16:19], v[172:175], v[208:211], v[16:19]
	v_mfma_f32_16x16x32_bf16 v[8:11], v[184:187], v[208:211], v[8:11]
	v_mfma_f32_16x16x32_bf16 v[4:7], v[172:175], v[216:219], v[4:7]
	v_mfma_f32_16x16x32_bf16 v[0:3], v[184:187], v[216:219], v[0:3]
	s_barrier
; __device__ __forceinline__ unsigned cvt_pk_bf16(float lo, float hi) { unsigned r; asm volatile("v_cvt_pk_bf16_f32 %0, %1, %2" : "=v"(r) : "v"(lo), "v"(hi)); return r; }
; #define PG8_WAIT_V(n) asm volatile("s_waitcnt vmcnt(" #n ")" ::: "memory")
; #define PG8_BAR __builtin_amdgcn_s_barrier()
;     __device__ __forceinline__ void operator()(const f32x4 (&acc)[2][2][4][2], const Unit& u, int wr, int wc, int fr, int fq) const {
;         const int row0 = u.pm * BM + wr * 64 + fr; const int col0 = u.pn * BM + wc * 32 + 8 * fq;
; #pragma unroll
;         for (int ai = 0; ai < 2; ++ai)
; #pragma unroll
;             for (int m = 0; m < 4; ++m) { bf16_t* rowp = O + (size_t)(row0 + ai * HALF + m * 16) * ldc + col0;
; #pragma unroll
;                 for (int bj = 0; bj < 2; ++bj) { const f32x4 v0 = acc[ai][bj][m][0], v1 = acc[ai][bj][m][1];
;                     u32x4 w; w.x = cvt_pk_bf16(v0[0], v0[1]); w.y = cvt_pk_bf16(v0[2], v0[3]); w.z = cvt_pk_bf16(v1[0], v1[1]); w.w = cvt_pk_bf16(v1[2], v1[3]);
;                     *(u32x4*)(rowp + bj * HALF) = w; } }
; template <class Epi, class Sched, bool ALIGN_EPI = false, bool SP2 = false>
; __device__ __forceinline__ void gemm_phase(PG8_LAS unsigned char* lds, const Gemm g, const Sched& S, const Epi& E) {
;     ...
;         if constexpr (!Epi::AFTER_DRAIN) { E(acc, cur, wr, wc, fr, fq); S.done(cur); }
;         if (!has_next) break;
; #pragma unroll
;         for (int a = 0; a < 2; ++a)
; #pragma unroll
;             for (int b = 0; b < 2; ++b)
; #pragma unroll
;                 for (int m = 0; m < 4; ++m)
; #pragma unroll
;                     for (int n = 0; n < 2; ++n) acc[a][b][m][n] = (f32x4){0.f, 0.f, 0.f, 0.f};
;         cur = nxt; cA = nA; cB = nB; ++ui;
;         if constexpr (ALIGN_EPI) { if (wr == 1) PG8_BAR; }
;     }
;     PG8_WAIT_V(0);
;     if constexpr (!ALIGN_EPI) { if (wr == 0) PG8_BAR; }
	s_setprio 1
	s_add_i32 s67, s67, 2
	s_add_u32 s65, s65, 0x100
	s_addc_u32 s66, s66, 0
	s_cmpk_gt_u32 s67, 0x55
	s_mov_b64 s[26:27], s[34:35]
	s_cbranch_scc0 .LBB0_552
	v_lshl_add_u32 v152, s63, 8, v146
	v_lshl_or_b32 v144, s64, 8, v148
	v_ashrrev_i32_e32 v153, 31, v152
	v_ashrrev_i32_e32 v145, 31, v144
	v_lshlrev_b64 v[154:155], 12, v[152:153]
	v_lshl_add_u64 v[154:155], s[90:91], 0, v[154:155]
	v_lshlrev_b64 v[156:157], 1, v[144:145]
	v_lshl_add_u64 v[144:145], v[154:155], 0, v[156:157]
	v_cvt_pk_bf16_f32 v124, v124, v125
	v_cvt_pk_bf16_f32 v125, v126, v127
	v_cvt_pk_bf16_f32 v126, v120, v121
	v_cvt_pk_bf16_f32 v127, v122, v123
	global_store_dwordx4 v[144:145], v[124:127], off
	v_cvt_pk_bf16_f32 v112, v112, v113
	v_cvt_pk_bf16_f32 v113, v114, v115
	v_cvt_pk_bf16_f32 v114, v104, v105
	v_or_b32_e32 v104, 16, v152
	v_ashrrev_i32_e32 v105, 31, v104
	v_lshlrev_b64 v[104:105], 12, v[104:105]
	v_lshl_add_u64 v[104:105], s[90:91], 0, v[104:105]
	v_cvt_pk_bf16_f32 v115, v106, v107
	global_store_dwordx4 v[144:145], v[112:115], off offset:256
	s_mov_b32 s64, s61
	s_mov_b32 s63, s62
	v_lshl_add_u64 v[112:113], v[104:105], 0, v[156:157]
	v_cvt_pk_bf16_f32 v104, v116, v117
	v_cvt_pk_bf16_f32 v105, v118, v119
	v_cvt_pk_bf16_f32 v106, v108, v109
	v_cvt_pk_bf16_f32 v107, v110, v111
	global_store_dwordx4 v[112:113], v[104:107], off
	v_cvt_pk_bf16_f32 v96, v96, v97
	v_cvt_pk_bf16_f32 v97, v98, v99
	v_cvt_pk_bf16_f32 v98, v88, v89
	v_or_b32_e32 v88, 32, v152
	v_ashrrev_i32_e32 v89, 31, v88
	v_lshlrev_b64 v[88:89], 12, v[88:89]
	v_lshl_add_u64 v[88:89], s[90:91], 0, v[88:89]
	v_cvt_pk_bf16_f32 v99, v90, v91
	global_store_dwordx4 v[112:113], v[96:99], off offset:256
	s_mov_b64 s[34:35], s[8:9]
	s_mov_b64 s[26:27], s[6:7]
	v_lshl_add_u64 v[96:97], v[88:89], 0, v[156:157]
	v_cvt_pk_bf16_f32 v88, v100, v101
	v_cvt_pk_bf16_f32 v89, v102, v103
	v_cvt_pk_bf16_f32 v90, v92, v93
	v_cvt_pk_bf16_f32 v91, v94, v95
	global_store_dwordx4 v[96:97], v[88:91], off
	v_cvt_pk_bf16_f32 v80, v80, v81
	v_cvt_pk_bf16_f32 v81, v82, v83
	v_cvt_pk_bf16_f32 v82, v72, v73
	v_or_b32_e32 v72, 48, v152
	v_ashrrev_i32_e32 v73, 31, v72
	v_lshlrev_b64 v[72:73], 12, v[72:73]
	v_lshl_add_u64 v[72:73], s[90:91], 0, v[72:73]
	v_cvt_pk_bf16_f32 v83, v74, v75
	global_store_dwordx4 v[96:97], v[80:83], off offset:256
	s_nop 1
	v_lshl_add_u64 v[80:81], v[72:73], 0, v[156:157]
	v_cvt_pk_bf16_f32 v72, v84, v85
	v_cvt_pk_bf16_f32 v73, v86, v87
	v_cvt_pk_bf16_f32 v74, v76, v77
	v_cvt_pk_bf16_f32 v75, v78, v79
	global_store_dwordx4 v[80:81], v[72:75], off
	v_cvt_pk_bf16_f32 v68, v68, v69
	v_cvt_pk_bf16_f32 v69, v70, v71
	v_cvt_pk_bf16_f32 v70, v64, v65
	v_cvt_pk_bf16_f32 v71, v66, v67
	global_store_dwordx4 v[80:81], v[68:71], off offset:256
	v_cvt_pk_bf16_f32 v60, v60, v61
	v_cvt_pk_bf16_f32 v61, v62, v63
	v_cvt_pk_bf16_f32 v62, v56, v57
	v_add_co_u32_e32 v56, vcc, s57, v144
	v_lshl_add_u64 v[64:65], v[144:145], 0, s[16:17]
	s_nop 0
	v_addc_co_u32_e32 v57, vcc, 0, v145, vcc
	v_cvt_pk_bf16_f32 v63, v58, v59
	global_store_dwordx4 v[56:57], v[60:63], off
	v_cvt_pk_bf16_f32 v48, v48, v49
	v_cvt_pk_bf16_f32 v49, v50, v51
	v_cvt_pk_bf16_f32 v50, v40, v41
	v_cvt_pk_bf16_f32 v51, v42, v43
	global_store_dwordx4 v[64:65], v[48:51], off offset:256
	v_cvt_pk_bf16_f32 v40, v52, v53
	v_cvt_pk_bf16_f32 v41, v54, v55
	v_cvt_pk_bf16_f32 v42, v44, v45
	v_add_co_u32_e32 v44, vcc, s58, v144
	s_nop 0
	v_lshl_add_u64 v[48:49], v[144:145], 0, s[20:21]
	v_addc_co_u32_e32 v45, vcc, 0, v145, vcc
	v_cvt_pk_bf16_f32 v43, v46, v47
	global_store_dwordx4 v[44:45], v[40:43], off
	v_cvt_pk_bf16_f32 v32, v32, v33
	v_cvt_pk_bf16_f32 v33, v34, v35
	v_cvt_pk_bf16_f32 v34, v24, v25
	v_cvt_pk_bf16_f32 v35, v26, v27
	global_store_dwordx4 v[48:49], v[32:35], off offset:256
	v_cvt_pk_bf16_f32 v24, v36, v37
	v_cvt_pk_bf16_f32 v25, v38, v39
	v_cvt_pk_bf16_f32 v26, v28, v29
	v_add_co_u32_e32 v28, vcc, s59, v144
	s_nop 0
	v_lshl_add_u64 v[32:33], v[144:145], 0, s[22:23]
	v_addc_co_u32_e32 v29, vcc, 0, v145, vcc
	v_cvt_pk_bf16_f32 v27, v30, v31
	global_store_dwordx4 v[28:29], v[24:27], off
	v_cvt_pk_bf16_f32 v16, v16, v17
	v_cvt_pk_bf16_f32 v17, v18, v19
	v_cvt_pk_bf16_f32 v18, v8, v9
	v_cvt_pk_bf16_f32 v19, v10, v11
	global_store_dwordx4 v[32:33], v[16:19], off offset:256
	v_cvt_pk_bf16_f32 v8, v20, v21
	v_cvt_pk_bf16_f32 v9, v22, v23
	v_cvt_pk_bf16_f32 v10, v12, v13
	v_add_co_u32_e32 v12, vcc, s60, v144
	s_nop 0
	v_lshl_add_u64 v[16:17], v[144:145], 0, s[24:25]
	v_addc_co_u32_e32 v13, vcc, 0, v145, vcc
	s_and_b64 vcc, exec, s[4:5]
	v_cvt_pk_bf16_f32 v11, v14, v15
	global_store_dwordx4 v[12:13], v[8:11], off
	v_cvt_pk_bf16_f32 v4, v4, v5
	v_cvt_pk_bf16_f32 v5, v6, v7
	v_cvt_pk_bf16_f32 v6, v0, v1
	v_cvt_pk_bf16_f32 v7, v2, v3
	global_store_dwordx4 v[16:17], v[4:7], off offset:256
	s_cbranch_vccz .LBB0_541
	s_waitcnt vmcnt(0)
	s_cmpk_gt_u32 s0, 0xff
	s_cbranch_scc1 .LBB0_556
	s_barrier
